# hand-written attention block loop (in-place accumulators, Q in regs, -m folded into MFMA C)
# speedup vs baseline: 1.0156x; 1.0156x over previous
.LBB0_465:
	v_add_f32_e32 v1, v1, v4
	v_mul_f32_e32 v4, 0x4f800000, v1
	v_cmp_gt_f32_e32 vcc, s70, v1
	v_add_f32_e32 v2, v2, v3
	v_mul_f32_e32 v3, 0x4f800000, v2
	v_cndmask_b32_e32 v1, v1, v4, vcc
	v_sqrt_f32_e32 v4, v1
	s_mul_i32 s82, s82, 0x88000
	s_lshl_b32 s81, s7, 1
	s_mov_b32 s42, s26
	v_add_u32_e32 v9, -1, v4
	v_fma_f32 v10, -v9, v4, v1
	v_cmp_ge_f32_e64 s[0:1], 0, v10
	v_add_u32_e32 v10, 1, v4
	s_mov_b32 s43, s27
	v_cndmask_b32_e64 v9, v4, v9, s[0:1]
	v_fma_f32 v4, -v10, v4, v1
	v_cmp_lt_f32_e64 s[0:1], 0, v4
	s_or_b32 s20, s5, 1
	s_and_b32 s4, s4, 15
	v_cndmask_b32_e64 v4, v9, v10, s[0:1]
	v_mul_f32_e32 v9, 0x37800000, v4
	v_cndmask_b32_e32 v4, v4, v9, vcc
	v_cmp_gt_f32_e32 vcc, s70, v2
	v_cmp_class_f32_e64 s[0:1], v1, v237
	s_lshl_b32 s4, s4, 10
	v_cndmask_b32_e32 v2, v2, v3, vcc
	v_sqrt_f32_e32 v3, v2
	v_cndmask_b32_e64 v1, v4, v1, s[0:1]
	s_waitcnt lgkmcnt(8)
	v_fma_f32 v1, v227, v1, v228
	v_mov_b32_e32 v224, 0
	v_add_u32_e32 v4, -1, v3
	v_fma_f32 v9, -v4, v3, v2
	v_cmp_ge_f32_e64 s[0:1], 0, v9
	v_add_u32_e32 v9, 1, v3
	s_mov_b32 s92, 0
	v_cndmask_b32_e64 v4, v3, v4, s[0:1]
	v_fma_f32 v3, -v9, v3, v2
	v_cmp_lt_f32_e64 s[0:1], 0, v3
	s_add_i32 s83, s83, 20
	s_add_i32 s84, s75, 4
	v_cndmask_b32_e64 v3, v4, v9, s[0:1]
	v_mul_f32_e32 v4, 0x37800000, v3
	v_cndmask_b32_e32 v3, v3, v4, vcc
	v_add_f32_e32 v4, v5, v6
	v_mul_f32_e32 v5, 0x4f800000, v4
	v_cmp_gt_f32_e32 vcc, s70, v4
	v_cmp_class_f32_e64 s[0:1], v2, v237
	v_mov_b32_e32 v225, v224
	v_cndmask_b32_e32 v4, v4, v5, vcc
	v_sqrt_f32_e32 v5, v4
	v_cndmask_b32_e64 v2, v3, v2, s[0:1]
	v_fma_f32 v2, v227, v2, v228
	v_max3_f32 v1, v1, 0, v2
	v_add_u32_e32 v2, -1, v5
	v_fma_f32 v3, -v2, v5, v4
	v_cmp_ge_f32_e64 s[0:1], 0, v3
	v_add_u32_e32 v3, 1, v5
	v_mov_b32_e32 v222, v224
	v_cndmask_b32_e64 v2, v5, v2, s[0:1]
	v_fma_f32 v5, -v3, v5, v4
	v_cmp_lt_f32_e64 s[0:1], 0, v5
	v_mov_b32_e32 v223, v224
	s_nop 0
	v_cndmask_b32_e64 v2, v2, v3, s[0:1]
	v_mul_f32_e32 v3, 0x37800000, v2
	s_lshl_b32 s0, s8, 1
	v_cndmask_b32_e32 v2, v2, v3, vcc
	v_cmp_class_f32_e32 vcc, v4, v237
	v_add_f32_e32 v3, v7, v8
	s_add_i32 s0, s0, s82
	v_cndmask_b32_e32 v2, v2, v4, vcc
	v_mul_f32_e32 v4, 0x4f800000, v3
	v_cmp_gt_f32_e32 vcc, s70, v3
	s_add_i32 s7, s0, 0x44000
	s_add_i32 s1, s0, 0x4c800
	v_cndmask_b32_e32 v3, v3, v4, vcc
	s_add_i32 s9, s0, 0x8800
	v_add_u32_e32 v80, 0x1000, v233
	v_add_u32_e32 v81, 0x1000, v235
	v_add_u32_e32 v82, 0x8800, v234
	v_add_u32_e32 v83, 0x44000, v234
	v_add_u32_e32 v84, 0x4c800, v234
	s_lshl_b32 s60, s6, 10
	s_add_i32 s60, s60, s81
	s_lshl_b32 s61, s6, 1
	s_add_i32 s61, s61, s82
	s_lshl_b32 s62, s8, 10
	s_add_i32 s62, s62, s81
	s_lshl_b32 s63, s8, 1
	s_add_i32 s63, s63, s82
	buffer_load_dwordx4 v[176:179], v233, s[24:27], s60 offen
	buffer_load_dwordx4 v[172:175], v235, s[24:27], s60 offen
	buffer_load_dwordx4 v[168:171], v80, s[24:27], s60 offen
	buffer_load_dwordx4 v[164:167], v81, s[24:27], s60 offen
	buffer_load_dwordx4 v[32:35], v234, s[40:43], s61 offen
	buffer_load_dwordx4 v[28:31], v82, s[40:43], s61 offen
	buffer_load_dwordx4 v[24:27], v83, s[40:43], s61 offen
	buffer_load_dwordx4 v[20:23], v84, s[40:43], s61 offen
	buffer_load_dwordx4 v[48:51], v233, s[24:27], s62 offen
	buffer_load_dwordx4 v[44:47], v235, s[24:27], s62 offen
	buffer_load_dwordx4 v[40:43], v80, s[24:27], s62 offen
	buffer_load_dwordx4 v[36:39], v81, s[24:27], s62 offen
	buffer_load_dwordx4 v[16:19], v234, s[40:43], s63 offen
	buffer_load_dwordx4 v[12:15], v82, s[40:43], s63 offen
	buffer_load_dwordx4 v[8:11], v83, s[40:43], s63 offen
	buffer_load_dwordx4 v[4:7], v84, s[40:43], s63 offen
	v_sqrt_f32_e32 v52, v3
	v_fma_f32 v2, v227, v2, v228
	v_add_u32_e32 v53, -1, v52
	v_fma_f32 v54, -v53, v52, v3
	v_cmp_ge_f32_e64 s[0:1], 0, v54
	v_add_u32_e32 v54, 1, v52
	s_nop 0
	v_cndmask_b32_e64 v53, v52, v53, s[0:1]
	v_fma_f32 v52, -v54, v52, v3
	v_cmp_lt_f32_e64 s[0:1], 0, v52
	s_nop 1
	v_cndmask_b32_e64 v52, v53, v54, s[0:1]
	v_mul_f32_e32 v53, 0x37800000, v52
	v_cndmask_b32_e32 v52, v52, v53, vcc
	v_cmp_class_f32_e32 vcc, v3, v237
	s_nop 1
	v_cndmask_b32_e32 v3, v52, v3, vcc
	v_fma_f32 v3, v227, v3, v228
	v_max3_f32 v239, v1, v2, v3
	v_add_u32_e32 v1, s59, v232
	v_sub_u32_e32 v1, v229, v1
	v_add_u32_e32 v2, 15, v1
	v_cmp_gt_u32_e64 s[0:1], 16, v2
	v_add_u32_e32 v2, 14, v1
	v_cmp_gt_u32_e64 s[6:7], 16, v2
	v_add_u32_e32 v2, 13, v1
	v_cmp_gt_u32_e64 s[8:9], 16, v2
	v_add_u32_e32 v2, 12, v1
	v_cmp_gt_u32_e64 s[10:11], 16, v2
	v_add_u32_e32 v2, 11, v1
	v_cmp_gt_u32_e64 s[12:13], 16, v2
	v_add_u32_e32 v2, 10, v1
	v_cmp_gt_u32_e64 s[14:15], 16, v2
	v_add_u32_e32 v2, 9, v1
	v_add_u32_e32 v1, 8, v1
	v_cmp_gt_u32_e64 s[18:19], 16, v1
	v_sub_u32_e64 v1, s20, 4 clamp
	v_cmp_gt_u32_e64 s[16:17], 16, v2
	v_readfirstlane_b32 s20, v1
	s_min_u32 s85, s20, 56
	s_or_b32 s20, s5, 2
	v_sub_u32_e64 v1, s20, 4 clamp
	s_or_b32 s5, s5, 3
	v_readfirstlane_b32 s20, v1
	v_sub_u32_e64 v1, s5, 4 clamp
	s_min_u32 s87, s20, 56
	v_readfirstlane_b32 s5, v1
	s_min_u32 s89, s5, 56
	s_lshl_b32 s5, s75, 8
	s_lshl_b32 s20, s59, 2
	s_or_b32 s5, s5, s20
	s_sub_i32 s4, s5, s4
	v_add_u32_e32 v240, s4, v236
	ds_read_b128 v[132:135], v231 offset:0
	ds_read_b128 v[136:139], v231 offset:1024
	ds_read_b128 v[140:143], v231 offset:2048
	ds_read_b128 v[144:147], v231 offset:3072
	ds_read_b128 v[148:151], v231 offset:4096
	ds_read_b128 v[152:155], v231 offset:5120
	ds_read_b128 v[156:159], v231 offset:6144
	ds_read_b128 v[160:163], v231 offset:7168
	v_xor_b32_e32 v76, 0x80000000, v239
	v_xor_b32_e32 v77, 0x80000000, v239
	v_xor_b32_e32 v78, 0x80000000, v239
	v_xor_b32_e32 v79, 0x80000000, v239
	v_cndmask_b32_e64 v180, 0, -1, s[0:1]
	v_cndmask_b32_e64 v181, 0, -1, s[6:7]
	v_cndmask_b32_e64 v182, 0, -1, s[8:9]
	v_cndmask_b32_e64 v183, 0, -1, s[10:11]
	v_cndmask_b32_e64 v184, 0, -1, s[12:13]
	v_cndmask_b32_e64 v185, 0, -1, s[14:15]
	v_cndmask_b32_e64 v186, 0, -1, s[16:17]
	v_cndmask_b32_e64 v187, 0, -1, s[18:19]
	v_mov_b32_e32 v96, 0
	v_mov_b32_e32 v97, 0
	v_mov_b32_e32 v98, 0
	v_mov_b32_e32 v99, 0
	v_mov_b32_e32 v88, 0
	v_mov_b32_e32 v89, 0
	v_mov_b32_e32 v90, 0
	v_mov_b32_e32 v91, 0
	v_mov_b32_e32 v72, 0
	v_mov_b32_e32 v73, 0
	v_mov_b32_e32 v74, 0
	v_mov_b32_e32 v75, 0
	v_mov_b32_e32 v68, 0
	v_mov_b32_e32 v69, 0
	v_mov_b32_e32 v70, 0
	v_mov_b32_e32 v71, 0
	v_mov_b32_e32 v222, 0
	v_mov_b32_e32 v64, 0
	v_mov_b32_e32 v65, 0
	v_mov_b32_e32 v66, 0
	v_mov_b32_e32 v67, 0
	v_mov_b32_e32 v60, 0
	v_mov_b32_e32 v61, 0
	v_mov_b32_e32 v62, 0
	v_mov_b32_e32 v63, 0
	v_mov_b32_e32 v56, 0
	v_mov_b32_e32 v57, 0
	v_mov_b32_e32 v58, 0
	v_mov_b32_e32 v59, 0
	v_mov_b32_e32 v52, 0
	v_mov_b32_e32 v53, 0
	v_mov_b32_e32 v54, 0
	v_mov_b32_e32 v55, 0
	v_mov_b32_e32 v223, 0
	v_mov_b32_e32 v128, 0
	v_mov_b32_e32 v129, 0
	v_mov_b32_e32 v130, 0
	v_mov_b32_e32 v131, 0
	v_mov_b32_e32 v124, 0
	v_mov_b32_e32 v125, 0
	v_mov_b32_e32 v126, 0
	v_mov_b32_e32 v127, 0
	v_mov_b32_e32 v120, 0
	v_mov_b32_e32 v121, 0
	v_mov_b32_e32 v122, 0
	v_mov_b32_e32 v123, 0
	v_mov_b32_e32 v116, 0
	v_mov_b32_e32 v117, 0
	v_mov_b32_e32 v118, 0
	v_mov_b32_e32 v119, 0
	v_mov_b32_e32 v224, 0
	v_mov_b32_e32 v112, 0
	v_mov_b32_e32 v113, 0
	v_mov_b32_e32 v114, 0
	v_mov_b32_e32 v115, 0
	v_mov_b32_e32 v108, 0
	v_mov_b32_e32 v109, 0
	v_mov_b32_e32 v110, 0
	v_mov_b32_e32 v111, 0
	v_mov_b32_e32 v104, 0
	v_mov_b32_e32 v105, 0
	v_mov_b32_e32 v106, 0
	v_mov_b32_e32 v107, 0
	v_mov_b32_e32 v100, 0
	v_mov_b32_e32 v101, 0
	v_mov_b32_e32 v102, 0
	v_mov_b32_e32 v103, 0
	v_mov_b32_e32 v225, 0
	s_mov_b32 s92, 0
	s_waitcnt lgkmcnt(0)
	s_cmp_eq_u32 s76, 8
	s_cbranch_scc1 .Latt_n8
	s_add_i32 s20, s92, 2
	s_min_i32 s20, s20, s80
	s_add_i32 s21, s20, s77
	s_lshl_b32 s21, s21, 6
	s_or_b32 s21, s21, s59
	s_sub_i32 s22, s20, s76
	s_lshl_b32 s22, s22, 5
	s_addk_i32 s22, 0x1000
	s_cmp_lt_i32 s20, s76
	s_cselect_b32 s20, s21, s22
	s_lshl_b32 s23, s20, 10
	s_add_i32 s23, s23, s81
	s_lshl_b32 s33, s20, 1
	s_add_i32 s33, s33, s82
	s_waitcnt vmcnt(12)
	ds_read2_b32 v[204:205], v240 offset0:192 offset1:193
	ds_read2_b32 v[206:207], v240 offset0:194 offset1:195
	ds_read2_b32 v[208:209], v240 offset0:196 offset1:197
	ds_read2_b32 v[210:211], v240 offset0:198 offset1:199
	v_mfma_f32_16x16x32_bf16 v[188:191], v[176:179], v[132:135], v[76:79]
	v_mfma_f32_16x16x32_bf16 v[192:195], v[168:171], v[132:135], v[76:79]
	v_mfma_f32_16x16x32_bf16 v[188:191], v[172:175], v[136:139], v[188:191]
	v_mfma_f32_16x16x32_bf16 v[192:195], v[164:167], v[136:139], v[192:195]
	buffer_load_dwordx4 v[176:179], v233, s[24:27], s23 offen
	buffer_load_dwordx4 v[172:175], v235, s[24:27], s23 offen
	buffer_load_dwordx4 v[168:171], v80, s[24:27], s23 offen
	buffer_load_dwordx4 v[164:167], v81, s[24:27], s23 offen
	s_waitcnt lgkmcnt(0)
	s_nop 1
	v_add_f32_e32 v188, v188, v204
	v_add_f32_e32 v189, v189, v205
	v_add_f32_e32 v190, v190, v206
	v_add_f32_e32 v191, v191, v207
	v_add_f32_e32 v192, v192, v208
	v_add_f32_e32 v193, v193, v209
	v_add_f32_e32 v194, v194, v210
	v_add_f32_e32 v195, v195, v211
	v_exp_f32_e32 v188, v188
	v_exp_f32_e32 v189, v189
	v_exp_f32_e32 v190, v190
	v_exp_f32_e32 v191, v191
	v_exp_f32_e32 v192, v192
	v_exp_f32_e32 v193, v193
	v_exp_f32_e32 v194, v194
	v_exp_f32_e32 v195, v195
	v_and_b32_e32 v188, v180, v188
	v_and_b32_e32 v189, v181, v189
	v_and_b32_e32 v190, v182, v190
	v_and_b32_e32 v191, v183, v191
	v_and_b32_e32 v192, v184, v192
	v_and_b32_e32 v193, v185, v193
	v_and_b32_e32 v194, v186, v194
	v_and_b32_e32 v195, v187, v195
	v_cvt_pk_bf16_f32 v246, v188, v189
	v_cvt_pk_bf16_f32 v247, v190, v191
	v_cvt_pk_bf16_f32 v248, v192, v193
	v_cvt_pk_bf16_f32 v249, v194, v195
	v_add_f32_e32 v1, v188, v189
	v_add_f32_e32 v2, v190, v191
	v_add_f32_e32 v3, v192, v193
	v_add_f32_e32 v85, v194, v195
	v_add_f32_e32 v1, v1, v2
	v_add_f32_e32 v3, v3, v85
	v_add_f32_e32 v1, v1, v3
	v_add_f32_e32 v222, v222, v1
	s_waitcnt vmcnt(12)
	v_mfma_f32_16x16x32_bf16 v[96:99], v[32:35], v[246:249], v[96:99]
	v_mfma_f32_16x16x32_bf16 v[88:91], v[28:31], v[246:249], v[88:91]
	v_mfma_f32_16x16x32_bf16 v[72:75], v[24:27], v[246:249], v[72:75]
	v_mfma_f32_16x16x32_bf16 v[68:71], v[20:23], v[246:249], v[68:71]
	buffer_load_dwordx4 v[32:35], v234, s[40:43], s33 offen
	buffer_load_dwordx4 v[28:31], v82, s[40:43], s33 offen
	buffer_load_dwordx4 v[24:27], v83, s[40:43], s33 offen
	buffer_load_dwordx4 v[20:23], v84, s[40:43], s33 offen
	v_add_u32_e32 v240, 0x100, v240
	s_add_i32 s92, s92, 1
	s_add_i32 s20, s92, 2
	s_min_i32 s20, s20, s80
	s_add_i32 s21, s20, s77
	s_lshl_b32 s21, s21, 6
	s_or_b32 s21, s21, s59
	s_sub_i32 s22, s20, s76
	s_lshl_b32 s22, s22, 5
	s_addk_i32 s22, 0x1000
	s_cmp_lt_i32 s20, s76
	s_cselect_b32 s20, s21, s22
	s_lshl_b32 s23, s20, 10
	s_add_i32 s23, s23, s81
	s_lshl_b32 s33, s20, 1
	s_add_i32 s33, s33, s82
	s_waitcnt vmcnt(12)
	ds_read2_b32 v[204:205], v240 offset0:192 offset1:193
	ds_read2_b32 v[206:207], v240 offset0:194 offset1:195
	ds_read2_b32 v[208:209], v240 offset0:196 offset1:197
	ds_read2_b32 v[210:211], v240 offset0:198 offset1:199
	ds_read2_b32 v[212:213], v240 offset0:128 offset1:129
	ds_read2_b32 v[214:215], v240 offset0:130 offset1:131
	ds_read2_b32 v[242:243], v240 offset0:132 offset1:133
	ds_read2_b32 v[244:245], v240 offset0:134 offset1:135
	v_mfma_f32_16x16x32_bf16 v[188:191], v[48:51], v[132:135], v[76:79]
	v_mfma_f32_16x16x32_bf16 v[192:195], v[40:43], v[132:135], v[76:79]
	v_mfma_f32_16x16x32_bf16 v[188:191], v[44:47], v[136:139], v[188:191]
	v_mfma_f32_16x16x32_bf16 v[192:195], v[36:39], v[136:139], v[192:195]
	v_mfma_f32_16x16x32_bf16 v[196:199], v[48:51], v[140:143], v[76:79]
	v_mfma_f32_16x16x32_bf16 v[200:203], v[40:43], v[140:143], v[76:79]
	v_mfma_f32_16x16x32_bf16 v[196:199], v[44:47], v[144:147], v[196:199]
	v_mfma_f32_16x16x32_bf16 v[200:203], v[36:39], v[144:147], v[200:203]
	buffer_load_dwordx4 v[48:51], v233, s[24:27], s23 offen
	buffer_load_dwordx4 v[44:47], v235, s[24:27], s23 offen
	buffer_load_dwordx4 v[40:43], v80, s[24:27], s23 offen
	buffer_load_dwordx4 v[36:39], v81, s[24:27], s23 offen
	s_waitcnt lgkmcnt(4)
	v_add_f32_e32 v188, v188, v204
	v_add_f32_e32 v189, v189, v205
	v_add_f32_e32 v190, v190, v206
	v_add_f32_e32 v191, v191, v207
	v_add_f32_e32 v192, v192, v208
	v_add_f32_e32 v193, v193, v209
	v_add_f32_e32 v194, v194, v210
	v_add_f32_e32 v195, v195, v211
	v_exp_f32_e32 v188, v188
	v_exp_f32_e32 v189, v189
	v_exp_f32_e32 v190, v190
	v_exp_f32_e32 v191, v191
	v_exp_f32_e32 v192, v192
	v_exp_f32_e32 v193, v193
	v_exp_f32_e32 v194, v194
	v_exp_f32_e32 v195, v195
	v_and_b32_e32 v188, v180, v188
	v_and_b32_e32 v189, v181, v189
	v_and_b32_e32 v190, v182, v190
	v_and_b32_e32 v191, v183, v191
	v_and_b32_e32 v192, v184, v192
	v_and_b32_e32 v193, v185, v193
	v_and_b32_e32 v194, v186, v194
	v_and_b32_e32 v195, v187, v195
	v_cvt_pk_bf16_f32 v246, v188, v189
	v_cvt_pk_bf16_f32 v247, v190, v191
	v_cvt_pk_bf16_f32 v248, v192, v193
	v_cvt_pk_bf16_f32 v249, v194, v195
	v_add_f32_e32 v1, v188, v189
	v_add_f32_e32 v2, v190, v191
	v_add_f32_e32 v3, v192, v193
	v_add_f32_e32 v85, v194, v195
	v_add_f32_e32 v1, v1, v2
	v_add_f32_e32 v3, v3, v85
	v_add_f32_e32 v1, v1, v3
	v_add_f32_e32 v222, v222, v1
	s_waitcnt vmcnt(12)
	s_waitcnt lgkmcnt(0)
	v_add_f32_e32 v196, v196, v212
	v_add_f32_e32 v197, v197, v213
	v_add_f32_e32 v198, v198, v214
	v_add_f32_e32 v199, v199, v215
	v_add_f32_e32 v200, v200, v242
	v_add_f32_e32 v201, v201, v243
	v_add_f32_e32 v202, v202, v244
	v_add_f32_e32 v203, v203, v245
	v_exp_f32_e32 v196, v196
	v_exp_f32_e32 v197, v197
	v_exp_f32_e32 v198, v198
	v_exp_f32_e32 v199, v199
	v_exp_f32_e32 v200, v200
	v_mfma_f32_16x16x32_bf16 v[96:99], v[16:19], v[246:249], v[96:99]
	v_exp_f32_e32 v201, v201
	v_exp_f32_e32 v202, v202
	v_exp_f32_e32 v203, v203
	v_and_b32_e32 v196, v180, v196
	v_and_b32_e32 v197, v181, v197
	v_mfma_f32_16x16x32_bf16 v[88:91], v[12:15], v[246:249], v[88:91]
	v_and_b32_e32 v198, v182, v198
	v_and_b32_e32 v199, v183, v199
	v_and_b32_e32 v200, v184, v200
	v_and_b32_e32 v201, v185, v201
	v_and_b32_e32 v202, v186, v202
	v_mfma_f32_16x16x32_bf16 v[72:75], v[8:11], v[246:249], v[72:75]
	v_and_b32_e32 v203, v187, v203
	v_cvt_pk_bf16_f32 v92, v196, v197
	v_cvt_pk_bf16_f32 v93, v198, v199
	v_cvt_pk_bf16_f32 v94, v200, v201
	v_cvt_pk_bf16_f32 v95, v202, v203
	v_mfma_f32_16x16x32_bf16 v[68:71], v[4:7], v[246:249], v[68:71]
	v_add_f32_e32 v86, v196, v197
	v_add_f32_e32 v87, v198, v199
	v_add_f32_e32 v220, v200, v201
	v_add_f32_e32 v221, v202, v203
	v_add_f32_e32 v86, v86, v87
	v_add_f32_e32 v220, v220, v221
	v_add_f32_e32 v86, v86, v220
	v_add_f32_e32 v223, v223, v86
	v_mfma_f32_16x16x32_bf16 v[64:67], v[16:19], v[92:95], v[64:67]
	v_mfma_f32_16x16x32_bf16 v[60:63], v[12:15], v[92:95], v[60:63]
	v_mfma_f32_16x16x32_bf16 v[56:59], v[8:11], v[92:95], v[56:59]
	v_mfma_f32_16x16x32_bf16 v[52:55], v[4:7], v[92:95], v[52:55]
	buffer_load_dwordx4 v[16:19], v234, s[40:43], s33 offen
	buffer_load_dwordx4 v[12:15], v82, s[40:43], s33 offen
	buffer_load_dwordx4 v[8:11], v83, s[40:43], s33 offen
	buffer_load_dwordx4 v[4:7], v84, s[40:43], s33 offen
	v_add_u32_e32 v240, 0x100, v240
	s_add_i32 s92, s92, 1
	s_add_i32 s20, s92, 2
	s_min_i32 s20, s20, s80
	s_add_i32 s21, s20, s77
	s_lshl_b32 s21, s21, 6
	s_or_b32 s21, s21, s59
	s_sub_i32 s22, s20, s76
	s_lshl_b32 s22, s22, 5
	s_addk_i32 s22, 0x1000
	s_cmp_lt_i32 s20, s76
	s_cselect_b32 s20, s21, s22
	s_lshl_b32 s23, s20, 10
	s_add_i32 s23, s23, s81
	s_lshl_b32 s33, s20, 1
	s_add_i32 s33, s33, s82
	s_waitcnt vmcnt(12)
	ds_read2_b32 v[204:205], v240 offset0:192 offset1:193
	ds_read2_b32 v[206:207], v240 offset0:194 offset1:195
	ds_read2_b32 v[208:209], v240 offset0:196 offset1:197
	ds_read2_b32 v[210:211], v240 offset0:198 offset1:199
	ds_read2_b32 v[212:213], v240 offset0:128 offset1:129
	ds_read2_b32 v[214:215], v240 offset0:130 offset1:131
	ds_read2_b32 v[242:243], v240 offset0:132 offset1:133
	ds_read2_b32 v[244:245], v240 offset0:134 offset1:135
	v_mfma_f32_16x16x32_bf16 v[188:191], v[176:179], v[132:135], v[76:79]
	v_mfma_f32_16x16x32_bf16 v[192:195], v[168:171], v[132:135], v[76:79]
	v_mfma_f32_16x16x32_bf16 v[188:191], v[172:175], v[136:139], v[188:191]
	v_mfma_f32_16x16x32_bf16 v[192:195], v[164:167], v[136:139], v[192:195]
	v_mfma_f32_16x16x32_bf16 v[196:199], v[176:179], v[140:143], v[76:79]
	v_mfma_f32_16x16x32_bf16 v[200:203], v[168:171], v[140:143], v[76:79]
	v_mfma_f32_16x16x32_bf16 v[196:199], v[172:175], v[144:147], v[196:199]
	v_mfma_f32_16x16x32_bf16 v[200:203], v[164:167], v[144:147], v[200:203]
	s_waitcnt lgkmcnt(4)
	s_nop 1
	v_add_f32_e32 v188, v188, v204
	v_add_f32_e32 v189, v189, v205
	v_add_f32_e32 v190, v190, v206
	v_add_f32_e32 v191, v191, v207
	v_add_f32_e32 v192, v192, v208
	v_add_f32_e32 v193, v193, v209
	v_add_f32_e32 v194, v194, v210
	v_add_f32_e32 v195, v195, v211
	ds_read2_b32 v[204:205], v240 offset0:64 offset1:65
	ds_read2_b32 v[206:207], v240 offset0:66 offset1:67
	ds_read2_b32 v[208:209], v240 offset0:68 offset1:69
	ds_read2_b32 v[210:211], v240 offset0:70 offset1:71
	v_exp_f32_e32 v188, v188
	v_exp_f32_e32 v189, v189
	v_exp_f32_e32 v190, v190
	v_exp_f32_e32 v191, v191
	v_exp_f32_e32 v192, v192
	v_exp_f32_e32 v193, v193
	v_exp_f32_e32 v194, v194
	v_exp_f32_e32 v195, v195
	v_and_b32_e32 v188, v180, v188
	v_and_b32_e32 v189, v181, v189
	v_and_b32_e32 v190, v182, v190
	v_and_b32_e32 v191, v183, v191
	v_and_b32_e32 v192, v184, v192
	v_and_b32_e32 v193, v185, v193
	v_and_b32_e32 v194, v186, v194
	v_and_b32_e32 v195, v187, v195
	v_cvt_pk_bf16_f32 v246, v188, v189
	v_cvt_pk_bf16_f32 v247, v190, v191
	v_cvt_pk_bf16_f32 v248, v192, v193
	v_cvt_pk_bf16_f32 v249, v194, v195
	v_add_f32_e32 v1, v188, v189
	v_add_f32_e32 v2, v190, v191
	v_add_f32_e32 v3, v192, v193
	v_add_f32_e32 v85, v194, v195
	v_add_f32_e32 v1, v1, v2
	v_add_f32_e32 v3, v3, v85
	v_add_f32_e32 v1, v1, v3
	v_add_f32_e32 v222, v222, v1
	v_mfma_f32_16x16x32_bf16 v[188:191], v[176:179], v[148:151], v[76:79]
	v_mfma_f32_16x16x32_bf16 v[192:195], v[168:171], v[148:151], v[76:79]
	v_mfma_f32_16x16x32_bf16 v[188:191], v[172:175], v[152:155], v[188:191]
	v_mfma_f32_16x16x32_bf16 v[192:195], v[164:167], v[152:155], v[192:195]
	buffer_load_dwordx4 v[176:179], v233, s[24:27], s23 offen
	buffer_load_dwordx4 v[172:175], v235, s[24:27], s23 offen
	buffer_load_dwordx4 v[168:171], v80, s[24:27], s23 offen
	buffer_load_dwordx4 v[164:167], v81, s[24:27], s23 offen
	s_waitcnt vmcnt(12)
	s_waitcnt lgkmcnt(4)
	v_add_f32_e32 v196, v196, v212
	v_add_f32_e32 v197, v197, v213
	v_add_f32_e32 v198, v198, v214
	v_add_f32_e32 v199, v199, v215
	v_add_f32_e32 v200, v200, v242
	v_add_f32_e32 v201, v201, v243
	v_add_f32_e32 v202, v202, v244
	v_add_f32_e32 v203, v203, v245
	v_exp_f32_e32 v196, v196
	v_exp_f32_e32 v197, v197
	v_exp_f32_e32 v198, v198
	v_exp_f32_e32 v199, v199
	v_exp_f32_e32 v200, v200
	v_mfma_f32_16x16x32_bf16 v[96:99], v[32:35], v[246:249], v[96:99]
	v_exp_f32_e32 v201, v201
	v_exp_f32_e32 v202, v202
	v_exp_f32_e32 v203, v203
	v_and_b32_e32 v196, v180, v196
	v_and_b32_e32 v197, v181, v197
	v_mfma_f32_16x16x32_bf16 v[88:91], v[28:31], v[246:249], v[88:91]
	v_and_b32_e32 v198, v182, v198
	v_and_b32_e32 v199, v183, v199
	v_and_b32_e32 v200, v184, v200
	v_and_b32_e32 v201, v185, v201
	v_and_b32_e32 v202, v186, v202
	v_mfma_f32_16x16x32_bf16 v[72:75], v[24:27], v[246:249], v[72:75]
	v_and_b32_e32 v203, v187, v203
	v_cvt_pk_bf16_f32 v92, v196, v197
	v_cvt_pk_bf16_f32 v93, v198, v199
	v_cvt_pk_bf16_f32 v94, v200, v201
	v_cvt_pk_bf16_f32 v95, v202, v203
	v_mfma_f32_16x16x32_bf16 v[68:71], v[20:23], v[246:249], v[68:71]
	v_add_f32_e32 v86, v196, v197
	v_add_f32_e32 v87, v198, v199
	v_add_f32_e32 v220, v200, v201
	v_add_f32_e32 v221, v202, v203
	v_add_f32_e32 v86, v86, v87
	v_add_f32_e32 v220, v220, v221
	v_add_f32_e32 v86, v86, v220
	v_add_f32_e32 v223, v223, v86
	s_waitcnt lgkmcnt(0)
	v_add_f32_e32 v188, v188, v204
	v_add_f32_e32 v189, v189, v205
	v_add_f32_e32 v190, v190, v206
	v_add_f32_e32 v191, v191, v207
	v_add_f32_e32 v192, v192, v208
	v_add_f32_e32 v193, v193, v209
	v_add_f32_e32 v194, v194, v210
	v_add_f32_e32 v195, v195, v211
	v_exp_f32_e32 v188, v188
	v_exp_f32_e32 v189, v189
	v_exp_f32_e32 v190, v190
	v_exp_f32_e32 v191, v191
	v_exp_f32_e32 v192, v192
	v_mfma_f32_16x16x32_bf16 v[64:67], v[32:35], v[92:95], v[64:67]
	v_exp_f32_e32 v193, v193
	v_exp_f32_e32 v194, v194
	v_exp_f32_e32 v195, v195
	v_and_b32_e32 v188, v180, v188
	v_and_b32_e32 v189, v181, v189
	v_mfma_f32_16x16x32_bf16 v[60:63], v[28:31], v[92:95], v[60:63]
	v_and_b32_e32 v190, v182, v190
	v_and_b32_e32 v191, v183, v191
	v_and_b32_e32 v192, v184, v192
	v_and_b32_e32 v193, v185, v193
	v_and_b32_e32 v194, v186, v194
	v_mfma_f32_16x16x32_bf16 v[56:59], v[24:27], v[92:95], v[56:59]
	v_and_b32_e32 v195, v187, v195
	v_cvt_pk_bf16_f32 v246, v188, v189
	v_cvt_pk_bf16_f32 v247, v190, v191
	v_cvt_pk_bf16_f32 v248, v192, v193
	v_cvt_pk_bf16_f32 v249, v194, v195
	v_mfma_f32_16x16x32_bf16 v[52:55], v[20:23], v[92:95], v[52:55]
	v_add_f32_e32 v1, v188, v189
	v_add_f32_e32 v2, v190, v191
	v_add_f32_e32 v3, v192, v193
	v_add_f32_e32 v85, v194, v195
	v_add_f32_e32 v1, v1, v2
	v_add_f32_e32 v3, v3, v85
	v_add_f32_e32 v1, v1, v3
	v_add_f32_e32 v224, v224, v1
	v_mfma_f32_16x16x32_bf16 v[128:131], v[32:35], v[246:249], v[128:131]
	v_mfma_f32_16x16x32_bf16 v[124:127], v[28:31], v[246:249], v[124:127]
	v_mfma_f32_16x16x32_bf16 v[120:123], v[24:27], v[246:249], v[120:123]
	v_mfma_f32_16x16x32_bf16 v[116:119], v[20:23], v[246:249], v[116:119]
	buffer_load_dwordx4 v[32:35], v234, s[40:43], s33 offen
	buffer_load_dwordx4 v[28:31], v82, s[40:43], s33 offen
	buffer_load_dwordx4 v[24:27], v83, s[40:43], s33 offen
	buffer_load_dwordx4 v[20:23], v84, s[40:43], s33 offen
	v_add_u32_e32 v240, 0x100, v240
	s_add_i32 s92, s92, 1
	s_mov_b32 s91, 5
	s_branch .Latt_FB
.Latt_n8:
	s_mov_b32 s91, 8
.Latt_FA:
	s_add_i32 s20, s92, 2
	s_min_i32 s20, s20, s80
	s_add_i32 s21, s20, s77
	s_lshl_b32 s21, s21, 6
	s_or_b32 s21, s21, s59
	s_sub_i32 s22, s20, s76
	s_lshl_b32 s22, s22, 5
	s_addk_i32 s22, 0x1000
	s_cmp_lt_i32 s20, s76
	s_cselect_b32 s20, s21, s22
	s_lshl_b32 s23, s20, 10
	s_add_i32 s23, s23, s81
	s_lshl_b32 s33, s20, 1
	s_add_i32 s33, s33, s82
	s_waitcnt vmcnt(12)
	ds_read2_b32 v[204:205], v240 offset0:192 offset1:193
	ds_read2_b32 v[206:207], v240 offset0:194 offset1:195
	ds_read2_b32 v[208:209], v240 offset0:196 offset1:197
	ds_read2_b32 v[210:211], v240 offset0:198 offset1:199
	ds_read2_b32 v[212:213], v240 offset0:128 offset1:129
	ds_read2_b32 v[214:215], v240 offset0:130 offset1:131
	ds_read2_b32 v[242:243], v240 offset0:132 offset1:133
	ds_read2_b32 v[244:245], v240 offset0:134 offset1:135
	v_mfma_f32_16x16x32_bf16 v[188:191], v[176:179], v[132:135], v[76:79]
	v_mfma_f32_16x16x32_bf16 v[192:195], v[168:171], v[132:135], v[76:79]
	v_mfma_f32_16x16x32_bf16 v[188:191], v[172:175], v[136:139], v[188:191]
	v_mfma_f32_16x16x32_bf16 v[192:195], v[164:167], v[136:139], v[192:195]
	v_mfma_f32_16x16x32_bf16 v[196:199], v[176:179], v[140:143], v[76:79]
	v_mfma_f32_16x16x32_bf16 v[200:203], v[168:171], v[140:143], v[76:79]
	v_mfma_f32_16x16x32_bf16 v[196:199], v[172:175], v[144:147], v[196:199]
	v_mfma_f32_16x16x32_bf16 v[200:203], v[164:167], v[144:147], v[200:203]
	s_waitcnt lgkmcnt(4)
	s_nop 1
	v_add_f32_e32 v188, v188, v204
	v_add_f32_e32 v189, v189, v205
	v_add_f32_e32 v190, v190, v206
	v_add_f32_e32 v191, v191, v207
	v_add_f32_e32 v192, v192, v208
	v_add_f32_e32 v193, v193, v209
	v_add_f32_e32 v194, v194, v210
	v_add_f32_e32 v195, v195, v211
	ds_read2_b32 v[204:205], v240 offset0:64 offset1:65
	ds_read2_b32 v[206:207], v240 offset0:66 offset1:67
	ds_read2_b32 v[208:209], v240 offset0:68 offset1:69
	ds_read2_b32 v[210:211], v240 offset0:70 offset1:71
	v_exp_f32_e32 v188, v188
	v_exp_f32_e32 v189, v189
	v_exp_f32_e32 v190, v190
	v_exp_f32_e32 v191, v191
	v_exp_f32_e32 v192, v192
	v_exp_f32_e32 v193, v193
	v_exp_f32_e32 v194, v194
	v_exp_f32_e32 v195, v195
	v_and_b32_e32 v188, v180, v188
	v_and_b32_e32 v189, v181, v189
	v_and_b32_e32 v190, v182, v190
	v_and_b32_e32 v191, v183, v191
	v_and_b32_e32 v192, v184, v192
	v_and_b32_e32 v193, v185, v193
	v_and_b32_e32 v194, v186, v194
	v_and_b32_e32 v195, v187, v195
	v_cvt_pk_bf16_f32 v246, v188, v189
	v_cvt_pk_bf16_f32 v247, v190, v191
	v_cvt_pk_bf16_f32 v248, v192, v193
	v_cvt_pk_bf16_f32 v249, v194, v195
	v_add_f32_e32 v1, v188, v189
	v_add_f32_e32 v2, v190, v191
	v_add_f32_e32 v3, v192, v193
	v_add_f32_e32 v85, v194, v195
	v_add_f32_e32 v1, v1, v2
	v_add_f32_e32 v3, v3, v85
	v_add_f32_e32 v1, v1, v3
	v_add_f32_e32 v222, v222, v1
	v_mfma_f32_16x16x32_bf16 v[188:191], v[176:179], v[148:151], v[76:79]
	v_mfma_f32_16x16x32_bf16 v[192:195], v[168:171], v[148:151], v[76:79]
	v_mfma_f32_16x16x32_bf16 v[188:191], v[172:175], v[152:155], v[188:191]
	v_mfma_f32_16x16x32_bf16 v[192:195], v[164:167], v[152:155], v[192:195]
	s_waitcnt vmcnt(8)
	s_waitcnt lgkmcnt(4)
	v_add_f32_e32 v196, v196, v212
	v_add_f32_e32 v197, v197, v213
	v_add_f32_e32 v198, v198, v214
	v_add_f32_e32 v199, v199, v215
	v_add_f32_e32 v200, v200, v242
	v_add_f32_e32 v201, v201, v243
	v_add_f32_e32 v202, v202, v244
	v_add_f32_e32 v203, v203, v245
	ds_read2_b32 v[212:213], v240 offset0:0 offset1:1
	ds_read2_b32 v[214:215], v240 offset0:2 offset1:3
	ds_read2_b32 v[242:243], v240 offset0:4 offset1:5
	ds_read2_b32 v[244:245], v240 offset0:6 offset1:7
	v_exp_f32_e32 v196, v196
	v_exp_f32_e32 v197, v197
	v_exp_f32_e32 v198, v198
	v_exp_f32_e32 v199, v199
	v_exp_f32_e32 v200, v200
	v_mfma_f32_16x16x32_bf16 v[96:99], v[32:35], v[246:249], v[96:99]
	v_exp_f32_e32 v201, v201
	v_exp_f32_e32 v202, v202
	v_exp_f32_e32 v203, v203
	v_and_b32_e32 v196, v180, v196
	v_and_b32_e32 v197, v181, v197
	v_mfma_f32_16x16x32_bf16 v[88:91], v[28:31], v[246:249], v[88:91]
	v_and_b32_e32 v198, v182, v198
	v_and_b32_e32 v199, v183, v199
	v_and_b32_e32 v200, v184, v200
	v_and_b32_e32 v201, v185, v201
	v_and_b32_e32 v202, v186, v202
	v_mfma_f32_16x16x32_bf16 v[72:75], v[24:27], v[246:249], v[72:75]
	v_and_b32_e32 v203, v187, v203
	v_cvt_pk_bf16_f32 v92, v196, v197
	v_cvt_pk_bf16_f32 v93, v198, v199
	v_cvt_pk_bf16_f32 v94, v200, v201
	v_cvt_pk_bf16_f32 v95, v202, v203
	v_mfma_f32_16x16x32_bf16 v[68:71], v[20:23], v[246:249], v[68:71]
	v_add_f32_e32 v86, v196, v197
	v_add_f32_e32 v87, v198, v199
	v_add_f32_e32 v220, v200, v201
	v_add_f32_e32 v221, v202, v203
	v_add_f32_e32 v86, v86, v87
	v_add_f32_e32 v220, v220, v221
	v_add_f32_e32 v86, v86, v220
	v_add_f32_e32 v223, v223, v86
	v_mfma_f32_16x16x32_bf16 v[196:199], v[176:179], v[156:159], v[76:79]
	v_mfma_f32_16x16x32_bf16 v[200:203], v[168:171], v[156:159], v[76:79]
	v_mfma_f32_16x16x32_bf16 v[196:199], v[172:175], v[160:163], v[196:199]
	v_mfma_f32_16x16x32_bf16 v[200:203], v[164:167], v[160:163], v[200:203]
	buffer_load_dwordx4 v[176:179], v233, s[24:27], s23 offen
	buffer_load_dwordx4 v[172:175], v235, s[24:27], s23 offen
	buffer_load_dwordx4 v[168:171], v80, s[24:27], s23 offen
	buffer_load_dwordx4 v[164:167], v81, s[24:27], s23 offen
	s_waitcnt lgkmcnt(4)
	v_add_f32_e32 v188, v188, v204
	v_add_f32_e32 v189, v189, v205
	v_add_f32_e32 v190, v190, v206
	v_add_f32_e32 v191, v191, v207
	v_add_f32_e32 v192, v192, v208
	v_add_f32_e32 v193, v193, v209
	v_add_f32_e32 v194, v194, v210
	v_add_f32_e32 v195, v195, v211
	v_exp_f32_e32 v188, v188
	v_exp_f32_e32 v189, v189
	v_exp_f32_e32 v190, v190
	v_exp_f32_e32 v191, v191
	v_exp_f32_e32 v192, v192
	v_mfma_f32_16x16x32_bf16 v[64:67], v[32:35], v[92:95], v[64:67]
	v_exp_f32_e32 v193, v193
	v_exp_f32_e32 v194, v194
	v_exp_f32_e32 v195, v195
	v_and_b32_e32 v188, v180, v188
	v_and_b32_e32 v189, v181, v189
	v_mfma_f32_16x16x32_bf16 v[60:63], v[28:31], v[92:95], v[60:63]
	v_and_b32_e32 v190, v182, v190
	v_and_b32_e32 v191, v183, v191
	v_and_b32_e32 v192, v184, v192
	v_and_b32_e32 v193, v185, v193
	v_and_b32_e32 v194, v186, v194
	v_mfma_f32_16x16x32_bf16 v[56:59], v[24:27], v[92:95], v[56:59]
	v_and_b32_e32 v195, v187, v195
	v_cvt_pk_bf16_f32 v246, v188, v189
	v_cvt_pk_bf16_f32 v247, v190, v191
	v_cvt_pk_bf16_f32 v248, v192, v193
	v_cvt_pk_bf16_f32 v249, v194, v195
	v_mfma_f32_16x16x32_bf16 v[52:55], v[20:23], v[92:95], v[52:55]
	v_add_f32_e32 v1, v188, v189
	v_add_f32_e32 v2, v190, v191
	v_add_f32_e32 v3, v192, v193
	v_add_f32_e32 v85, v194, v195
	v_add_f32_e32 v1, v1, v2
	v_add_f32_e32 v3, v3, v85
	v_add_f32_e32 v1, v1, v3
	v_add_f32_e32 v224, v224, v1
	s_waitcnt lgkmcnt(0)
	v_add_f32_e32 v196, v196, v212
	v_add_f32_e32 v197, v197, v213
	v_add_f32_e32 v198, v198, v214
	v_add_f32_e32 v199, v199, v215
	v_add_f32_e32 v200, v200, v242
	v_add_f32_e32 v201, v201, v243
	v_add_f32_e32 v202, v202, v244
	v_add_f32_e32 v203, v203, v245
	v_exp_f32_e32 v196, v196
	v_exp_f32_e32 v197, v197
	v_exp_f32_e32 v198, v198
	v_exp_f32_e32 v199, v199
	v_exp_f32_e32 v200, v200
	v_mfma_f32_16x16x32_bf16 v[128:131], v[32:35], v[246:249], v[128:131]
	v_exp_f32_e32 v201, v201
	v_exp_f32_e32 v202, v202
	v_exp_f32_e32 v203, v203
	v_and_b32_e32 v196, v180, v196
	v_and_b32_e32 v197, v181, v197
	v_mfma_f32_16x16x32_bf16 v[124:127], v[28:31], v[246:249], v[124:127]
	v_and_b32_e32 v198, v182, v198
	v_and_b32_e32 v199, v183, v199
	v_and_b32_e32 v200, v184, v200
	v_and_b32_e32 v201, v185, v201
	v_and_b32_e32 v202, v186, v202
	v_mfma_f32_16x16x32_bf16 v[120:123], v[24:27], v[246:249], v[120:123]
	v_and_b32_e32 v203, v187, v203
	v_cvt_pk_bf16_f32 v92, v196, v197
	v_cvt_pk_bf16_f32 v93, v198, v199
	v_cvt_pk_bf16_f32 v94, v200, v201
	v_cvt_pk_bf16_f32 v95, v202, v203
	v_mfma_f32_16x16x32_bf16 v[116:119], v[20:23], v[246:249], v[116:119]
	v_add_f32_e32 v86, v196, v197
	v_add_f32_e32 v87, v198, v199
	v_add_f32_e32 v220, v200, v201
	v_add_f32_e32 v221, v202, v203
	v_add_f32_e32 v86, v86, v87
	v_add_f32_e32 v220, v220, v221
	v_add_f32_e32 v86, v86, v220
	v_add_f32_e32 v225, v225, v86
	v_mfma_f32_16x16x32_bf16 v[112:115], v[32:35], v[92:95], v[112:115]
	v_mfma_f32_16x16x32_bf16 v[108:111], v[28:31], v[92:95], v[108:111]
	v_mfma_f32_16x16x32_bf16 v[104:107], v[24:27], v[92:95], v[104:107]
	v_mfma_f32_16x16x32_bf16 v[100:103], v[20:23], v[92:95], v[100:103]
	buffer_load_dwordx4 v[32:35], v234, s[40:43], s33 offen
	buffer_load_dwordx4 v[28:31], v82, s[40:43], s33 offen
	buffer_load_dwordx4 v[24:27], v83, s[40:43], s33 offen
	buffer_load_dwordx4 v[20:23], v84, s[40:43], s33 offen
	v_add_u32_e32 v240, 0x100, v240
	s_add_i32 s92, s92, 1
	s_sub_u32 s91, s91, 1
.Latt_FB:
	s_add_i32 s20, s92, 2
	s_min_i32 s20, s20, s80
	s_add_i32 s21, s20, s77
	s_lshl_b32 s21, s21, 6
	s_or_b32 s21, s21, s59
	s_sub_i32 s22, s20, s76
	s_lshl_b32 s22, s22, 5
	s_addk_i32 s22, 0x1000
	s_cmp_lt_i32 s20, s76
	s_cselect_b32 s20, s21, s22
	s_lshl_b32 s23, s20, 10
	s_add_i32 s23, s23, s81
	s_lshl_b32 s33, s20, 1
	s_add_i32 s33, s33, s82
	s_waitcnt vmcnt(12)
	ds_read2_b32 v[204:205], v240 offset0:192 offset1:193
	ds_read2_b32 v[206:207], v240 offset0:194 offset1:195
	ds_read2_b32 v[208:209], v240 offset0:196 offset1:197
	ds_read2_b32 v[210:211], v240 offset0:198 offset1:199
	ds_read2_b32 v[212:213], v240 offset0:128 offset1:129
	ds_read2_b32 v[214:215], v240 offset0:130 offset1:131
	ds_read2_b32 v[242:243], v240 offset0:132 offset1:133
	ds_read2_b32 v[244:245], v240 offset0:134 offset1:135
	v_mfma_f32_16x16x32_bf16 v[188:191], v[48:51], v[132:135], v[76:79]
	v_mfma_f32_16x16x32_bf16 v[192:195], v[40:43], v[132:135], v[76:79]
	v_mfma_f32_16x16x32_bf16 v[188:191], v[44:47], v[136:139], v[188:191]
	v_mfma_f32_16x16x32_bf16 v[192:195], v[36:39], v[136:139], v[192:195]
	v_mfma_f32_16x16x32_bf16 v[196:199], v[48:51], v[140:143], v[76:79]
	v_mfma_f32_16x16x32_bf16 v[200:203], v[40:43], v[140:143], v[76:79]
	v_mfma_f32_16x16x32_bf16 v[196:199], v[44:47], v[144:147], v[196:199]
	v_mfma_f32_16x16x32_bf16 v[200:203], v[36:39], v[144:147], v[200:203]
	s_waitcnt lgkmcnt(4)
	s_nop 1
	v_add_f32_e32 v188, v188, v204
	v_add_f32_e32 v189, v189, v205
	v_add_f32_e32 v190, v190, v206
	v_add_f32_e32 v191, v191, v207
	v_add_f32_e32 v192, v192, v208
	v_add_f32_e32 v193, v193, v209
	v_add_f32_e32 v194, v194, v210
	v_add_f32_e32 v195, v195, v211
	ds_read2_b32 v[204:205], v240 offset0:64 offset1:65
	ds_read2_b32 v[206:207], v240 offset0:66 offset1:67
	ds_read2_b32 v[208:209], v240 offset0:68 offset1:69
	ds_read2_b32 v[210:211], v240 offset0:70 offset1:71
	v_exp_f32_e32 v188, v188
	v_exp_f32_e32 v189, v189
	v_exp_f32_e32 v190, v190
	v_exp_f32_e32 v191, v191
	v_exp_f32_e32 v192, v192
	v_exp_f32_e32 v193, v193
	v_exp_f32_e32 v194, v194
	v_exp_f32_e32 v195, v195
	v_and_b32_e32 v188, v180, v188
	v_and_b32_e32 v189, v181, v189
	v_and_b32_e32 v190, v182, v190
	v_and_b32_e32 v191, v183, v191
	v_and_b32_e32 v192, v184, v192
	v_and_b32_e32 v193, v185, v193
	v_and_b32_e32 v194, v186, v194
	v_and_b32_e32 v195, v187, v195
	v_cvt_pk_bf16_f32 v246, v188, v189
	v_cvt_pk_bf16_f32 v247, v190, v191
	v_cvt_pk_bf16_f32 v248, v192, v193
	v_cvt_pk_bf16_f32 v249, v194, v195
	v_add_f32_e32 v1, v188, v189
	v_add_f32_e32 v2, v190, v191
	v_add_f32_e32 v3, v192, v193
	v_add_f32_e32 v85, v194, v195
	v_add_f32_e32 v1, v1, v2
	v_add_f32_e32 v3, v3, v85
	v_add_f32_e32 v1, v1, v3
	v_add_f32_e32 v222, v222, v1
	v_mfma_f32_16x16x32_bf16 v[188:191], v[48:51], v[148:151], v[76:79]
	v_mfma_f32_16x16x32_bf16 v[192:195], v[40:43], v[148:151], v[76:79]
	v_mfma_f32_16x16x32_bf16 v[188:191], v[44:47], v[152:155], v[188:191]
	v_mfma_f32_16x16x32_bf16 v[192:195], v[36:39], v[152:155], v[192:195]
	s_waitcnt vmcnt(8)
	s_waitcnt lgkmcnt(4)
	v_add_f32_e32 v196, v196, v212
	v_add_f32_e32 v197, v197, v213
	v_add_f32_e32 v198, v198, v214
	v_add_f32_e32 v199, v199, v215
	v_add_f32_e32 v200, v200, v242
	v_add_f32_e32 v201, v201, v243
	v_add_f32_e32 v202, v202, v244
	v_add_f32_e32 v203, v203, v245
	ds_read2_b32 v[212:213], v240 offset0:0 offset1:1
	ds_read2_b32 v[214:215], v240 offset0:2 offset1:3
	ds_read2_b32 v[242:243], v240 offset0:4 offset1:5
	ds_read2_b32 v[244:245], v240 offset0:6 offset1:7
	v_exp_f32_e32 v196, v196
	v_exp_f32_e32 v197, v197
	v_exp_f32_e32 v198, v198
	v_exp_f32_e32 v199, v199
	v_exp_f32_e32 v200, v200
	v_mfma_f32_16x16x32_bf16 v[96:99], v[16:19], v[246:249], v[96:99]
	v_exp_f32_e32 v201, v201
	v_exp_f32_e32 v202, v202
	v_exp_f32_e32 v203, v203
	v_and_b32_e32 v196, v180, v196
	v_and_b32_e32 v197, v181, v197
	v_mfma_f32_16x16x32_bf16 v[88:91], v[12:15], v[246:249], v[88:91]
	v_and_b32_e32 v198, v182, v198
	v_and_b32_e32 v199, v183, v199
	v_and_b32_e32 v200, v184, v200
	v_and_b32_e32 v201, v185, v201
	v_and_b32_e32 v202, v186, v202
	v_mfma_f32_16x16x32_bf16 v[72:75], v[8:11], v[246:249], v[72:75]
	v_and_b32_e32 v203, v187, v203
	v_cvt_pk_bf16_f32 v92, v196, v197
	v_cvt_pk_bf16_f32 v93, v198, v199
	v_cvt_pk_bf16_f32 v94, v200, v201
	v_cvt_pk_bf16_f32 v95, v202, v203
	v_mfma_f32_16x16x32_bf16 v[68:71], v[4:7], v[246:249], v[68:71]
	v_add_f32_e32 v86, v196, v197
	v_add_f32_e32 v87, v198, v199
	v_add_f32_e32 v220, v200, v201
	v_add_f32_e32 v221, v202, v203
	v_add_f32_e32 v86, v86, v87
	v_add_f32_e32 v220, v220, v221
	v_add_f32_e32 v86, v86, v220
	v_add_f32_e32 v223, v223, v86
	v_mfma_f32_16x16x32_bf16 v[196:199], v[48:51], v[156:159], v[76:79]
	v_mfma_f32_16x16x32_bf16 v[200:203], v[40:43], v[156:159], v[76:79]
	v_mfma_f32_16x16x32_bf16 v[196:199], v[44:47], v[160:163], v[196:199]
	v_mfma_f32_16x16x32_bf16 v[200:203], v[36:39], v[160:163], v[200:203]
	buffer_load_dwordx4 v[48:51], v233, s[24:27], s23 offen
	buffer_load_dwordx4 v[44:47], v235, s[24:27], s23 offen
	buffer_load_dwordx4 v[40:43], v80, s[24:27], s23 offen
	buffer_load_dwordx4 v[36:39], v81, s[24:27], s23 offen
	s_waitcnt lgkmcnt(4)
	v_add_f32_e32 v188, v188, v204
	v_add_f32_e32 v189, v189, v205
	v_add_f32_e32 v190, v190, v206
	v_add_f32_e32 v191, v191, v207
	v_add_f32_e32 v192, v192, v208
	v_add_f32_e32 v193, v193, v209
	v_add_f32_e32 v194, v194, v210
	v_add_f32_e32 v195, v195, v211
	v_exp_f32_e32 v188, v188
	v_exp_f32_e32 v189, v189
	v_exp_f32_e32 v190, v190
	v_exp_f32_e32 v191, v191
	v_exp_f32_e32 v192, v192
	v_mfma_f32_16x16x32_bf16 v[64:67], v[16:19], v[92:95], v[64:67]
	v_exp_f32_e32 v193, v193
	v_exp_f32_e32 v194, v194
	v_exp_f32_e32 v195, v195
	v_and_b32_e32 v188, v180, v188
	v_and_b32_e32 v189, v181, v189
	v_mfma_f32_16x16x32_bf16 v[60:63], v[12:15], v[92:95], v[60:63]
	v_and_b32_e32 v190, v182, v190
	v_and_b32_e32 v191, v183, v191
	v_and_b32_e32 v192, v184, v192
	v_and_b32_e32 v193, v185, v193
	v_and_b32_e32 v194, v186, v194
	v_mfma_f32_16x16x32_bf16 v[56:59], v[8:11], v[92:95], v[56:59]
	v_and_b32_e32 v195, v187, v195
	v_cvt_pk_bf16_f32 v246, v188, v189
	v_cvt_pk_bf16_f32 v247, v190, v191
	v_cvt_pk_bf16_f32 v248, v192, v193
	v_cvt_pk_bf16_f32 v249, v194, v195
	v_mfma_f32_16x16x32_bf16 v[52:55], v[4:7], v[92:95], v[52:55]
	v_add_f32_e32 v1, v188, v189
	v_add_f32_e32 v2, v190, v191
	v_add_f32_e32 v3, v192, v193
	v_add_f32_e32 v85, v194, v195
	v_add_f32_e32 v1, v1, v2
	v_add_f32_e32 v3, v3, v85
	v_add_f32_e32 v1, v1, v3
	v_add_f32_e32 v224, v224, v1
	s_waitcnt lgkmcnt(0)
	v_add_f32_e32 v196, v196, v212
	v_add_f32_e32 v197, v197, v213
	v_add_f32_e32 v198, v198, v214
	v_add_f32_e32 v199, v199, v215
	v_add_f32_e32 v200, v200, v242
	v_add_f32_e32 v201, v201, v243
	v_add_f32_e32 v202, v202, v244
	v_add_f32_e32 v203, v203, v245
	v_exp_f32_e32 v196, v196
	v_exp_f32_e32 v197, v197
	v_exp_f32_e32 v198, v198
	v_exp_f32_e32 v199, v199
	v_exp_f32_e32 v200, v200
	v_mfma_f32_16x16x32_bf16 v[128:131], v[16:19], v[246:249], v[128:131]
	v_exp_f32_e32 v201, v201
	v_exp_f32_e32 v202, v202
	v_exp_f32_e32 v203, v203
	v_and_b32_e32 v196, v180, v196
	v_and_b32_e32 v197, v181, v197
	v_mfma_f32_16x16x32_bf16 v[124:127], v[12:15], v[246:249], v[124:127]
	v_and_b32_e32 v198, v182, v198
	v_and_b32_e32 v199, v183, v199
	v_and_b32_e32 v200, v184, v200
	v_and_b32_e32 v201, v185, v201
	v_and_b32_e32 v202, v186, v202
	v_mfma_f32_16x16x32_bf16 v[120:123], v[8:11], v[246:249], v[120:123]
	v_and_b32_e32 v203, v187, v203
	v_cvt_pk_bf16_f32 v92, v196, v197
	v_cvt_pk_bf16_f32 v93, v198, v199
	v_cvt_pk_bf16_f32 v94, v200, v201
	v_cvt_pk_bf16_f32 v95, v202, v203
	v_mfma_f32_16x16x32_bf16 v[116:119], v[4:7], v[246:249], v[116:119]
	v_add_f32_e32 v86, v196, v197
	v_add_f32_e32 v87, v198, v199
	v_add_f32_e32 v220, v200, v201
	v_add_f32_e32 v221, v202, v203
	v_add_f32_e32 v86, v86, v87
	v_add_f32_e32 v220, v220, v221
	v_add_f32_e32 v86, v86, v220
	v_add_f32_e32 v225, v225, v86
	v_mfma_f32_16x16x32_bf16 v[112:115], v[16:19], v[92:95], v[112:115]
	v_mfma_f32_16x16x32_bf16 v[108:111], v[12:15], v[92:95], v[108:111]
	v_mfma_f32_16x16x32_bf16 v[104:107], v[8:11], v[92:95], v[104:107]
	v_mfma_f32_16x16x32_bf16 v[100:103], v[4:7], v[92:95], v[100:103]
	buffer_load_dwordx4 v[16:19], v234, s[40:43], s33 offen
	buffer_load_dwordx4 v[12:15], v82, s[40:43], s33 offen
	buffer_load_dwordx4 v[8:11], v83, s[40:43], s33 offen
	buffer_load_dwordx4 v[4:7], v84, s[40:43], s33 offen
	v_add_u32_e32 v240, 0x100, v240
	s_add_i32 s92, s92, 1
	s_sub_u32 s91, s91, 1
	s_cmp_lg_u32 s91, 0
	s_cbranch_scc1 .Latt_FA
	s_cmp_eq_u32 s76, 8
	s_cbranch_scc1 .Latt_ctx8
	s_add_i32 s20, s92, 2
	s_min_i32 s20, s20, s80
	s_add_i32 s21, s20, s77
	s_lshl_b32 s21, s21, 6
	s_or_b32 s21, s21, s59
	s_sub_i32 s22, s20, s76
	s_lshl_b32 s22, s22, 5
	s_addk_i32 s22, 0x1000
	s_cmp_lt_i32 s20, s76
	s_cselect_b32 s20, s21, s22
	s_lshl_b32 s23, s20, 10
	s_add_i32 s23, s23, s81
	s_lshl_b32 s33, s20, 1
	s_add_i32 s33, s33, s82
	s_waitcnt vmcnt(12)
	ds_read2_b32 v[204:205], v240 offset0:128 offset1:129
	ds_read2_b32 v[206:207], v240 offset0:130 offset1:131
	ds_read2_b32 v[208:209], v240 offset0:132 offset1:133
	ds_read2_b32 v[210:211], v240 offset0:134 offset1:135
	ds_read2_b32 v[212:213], v240 offset0:64 offset1:65
	ds_read2_b32 v[214:215], v240 offset0:66 offset1:67
	ds_read2_b32 v[242:243], v240 offset0:68 offset1:69
	ds_read2_b32 v[244:245], v240 offset0:70 offset1:71
	v_mfma_f32_16x16x32_bf16 v[188:191], v[176:179], v[140:143], v[76:79]
	v_mfma_f32_16x16x32_bf16 v[192:195], v[168:171], v[140:143], v[76:79]
	v_mfma_f32_16x16x32_bf16 v[188:191], v[172:175], v[144:147], v[188:191]
	v_mfma_f32_16x16x32_bf16 v[192:195], v[164:167], v[144:147], v[192:195]
	v_mfma_f32_16x16x32_bf16 v[196:199], v[176:179], v[148:151], v[76:79]
	v_mfma_f32_16x16x32_bf16 v[200:203], v[168:171], v[148:151], v[76:79]
	v_mfma_f32_16x16x32_bf16 v[196:199], v[172:175], v[152:155], v[196:199]
	v_mfma_f32_16x16x32_bf16 v[200:203], v[164:167], v[152:155], v[200:203]
	s_waitcnt lgkmcnt(4)
	s_nop 1
	v_add_f32_e32 v188, v188, v204
	v_add_f32_e32 v189, v189, v205
	v_add_f32_e32 v190, v190, v206
	v_add_f32_e32 v191, v191, v207
	v_add_f32_e32 v192, v192, v208
	v_add_f32_e32 v193, v193, v209
	v_add_f32_e32 v194, v194, v210
	v_add_f32_e32 v195, v195, v211
	ds_read2_b32 v[204:205], v240 offset0:0 offset1:1
	ds_read2_b32 v[206:207], v240 offset0:2 offset1:3
	ds_read2_b32 v[208:209], v240 offset0:4 offset1:5
	ds_read2_b32 v[210:211], v240 offset0:6 offset1:7
	v_exp_f32_e32 v188, v188
	v_exp_f32_e32 v189, v189
	v_exp_f32_e32 v190, v190
	v_exp_f32_e32 v191, v191
	v_exp_f32_e32 v192, v192
	v_exp_f32_e32 v193, v193
	v_exp_f32_e32 v194, v194
	v_exp_f32_e32 v195, v195
	v_and_b32_e32 v188, v180, v188
	v_and_b32_e32 v189, v181, v189
	v_and_b32_e32 v190, v182, v190
	v_and_b32_e32 v191, v183, v191
	v_and_b32_e32 v192, v184, v192
	v_and_b32_e32 v193, v185, v193
	v_and_b32_e32 v194, v186, v194
	v_and_b32_e32 v195, v187, v195
	v_cvt_pk_bf16_f32 v246, v188, v189
	v_cvt_pk_bf16_f32 v247, v190, v191
	v_cvt_pk_bf16_f32 v248, v192, v193
	v_cvt_pk_bf16_f32 v249, v194, v195
	v_add_f32_e32 v1, v188, v189
	v_add_f32_e32 v2, v190, v191
	v_add_f32_e32 v3, v192, v193
	v_add_f32_e32 v85, v194, v195
	v_add_f32_e32 v1, v1, v2
	v_add_f32_e32 v3, v3, v85
	v_add_f32_e32 v1, v1, v3
	v_add_f32_e32 v223, v223, v1
	v_mfma_f32_16x16x32_bf16 v[188:191], v[176:179], v[156:159], v[76:79]
	v_mfma_f32_16x16x32_bf16 v[192:195], v[168:171], v[156:159], v[76:79]
	v_mfma_f32_16x16x32_bf16 v[188:191], v[172:175], v[160:163], v[188:191]
	v_mfma_f32_16x16x32_bf16 v[192:195], v[164:167], v[160:163], v[192:195]
	buffer_load_dwordx4 v[176:179], v233, s[24:27], s23 offen
	buffer_load_dwordx4 v[172:175], v235, s[24:27], s23 offen
	buffer_load_dwordx4 v[168:171], v80, s[24:27], s23 offen
	buffer_load_dwordx4 v[164:167], v81, s[24:27], s23 offen
	s_waitcnt vmcnt(12)
	s_waitcnt lgkmcnt(4)
	v_add_f32_e32 v196, v196, v212
	v_add_f32_e32 v197, v197, v213
	v_add_f32_e32 v198, v198, v214
	v_add_f32_e32 v199, v199, v215
	v_add_f32_e32 v200, v200, v242
	v_add_f32_e32 v201, v201, v243
	v_add_f32_e32 v202, v202, v244
	v_add_f32_e32 v203, v203, v245
	v_exp_f32_e32 v196, v196
	v_exp_f32_e32 v197, v197
	v_exp_f32_e32 v198, v198
	v_exp_f32_e32 v199, v199
	v_exp_f32_e32 v200, v200
	v_mfma_f32_16x16x32_bf16 v[64:67], v[32:35], v[246:249], v[64:67]
	v_exp_f32_e32 v201, v201
	v_exp_f32_e32 v202, v202
	v_exp_f32_e32 v203, v203
	v_and_b32_e32 v196, v180, v196
	v_and_b32_e32 v197, v181, v197
	v_mfma_f32_16x16x32_bf16 v[60:63], v[28:31], v[246:249], v[60:63]
	v_and_b32_e32 v198, v182, v198
	v_and_b32_e32 v199, v183, v199
	v_and_b32_e32 v200, v184, v200
	v_and_b32_e32 v201, v185, v201
	v_and_b32_e32 v202, v186, v202
	v_mfma_f32_16x16x32_bf16 v[56:59], v[24:27], v[246:249], v[56:59]
	v_and_b32_e32 v203, v187, v203
	v_cvt_pk_bf16_f32 v92, v196, v197
	v_cvt_pk_bf16_f32 v93, v198, v199
	v_cvt_pk_bf16_f32 v94, v200, v201
	v_cvt_pk_bf16_f32 v95, v202, v203
	v_mfma_f32_16x16x32_bf16 v[52:55], v[20:23], v[246:249], v[52:55]
	v_add_f32_e32 v86, v196, v197
	v_add_f32_e32 v87, v198, v199
	v_add_f32_e32 v220, v200, v201
	v_add_f32_e32 v221, v202, v203
	v_add_f32_e32 v86, v86, v87
	v_add_f32_e32 v220, v220, v221
	v_add_f32_e32 v86, v86, v220
	v_add_f32_e32 v224, v224, v86
	s_waitcnt lgkmcnt(0)
	v_add_f32_e32 v188, v188, v204
	v_add_f32_e32 v189, v189, v205
	v_add_f32_e32 v190, v190, v206
	v_add_f32_e32 v191, v191, v207
	v_add_f32_e32 v192, v192, v208
	v_add_f32_e32 v193, v193, v209
	v_add_f32_e32 v194, v194, v210
	v_add_f32_e32 v195, v195, v211
	v_exp_f32_e32 v188, v188
	v_exp_f32_e32 v189, v189
	v_exp_f32_e32 v190, v190
	v_exp_f32_e32 v191, v191
	v_exp_f32_e32 v192, v192
	v_mfma_f32_16x16x32_bf16 v[128:131], v[32:35], v[92:95], v[128:131]
	v_exp_f32_e32 v193, v193
	v_exp_f32_e32 v194, v194
	v_exp_f32_e32 v195, v195
	v_and_b32_e32 v188, v180, v188
	v_and_b32_e32 v189, v181, v189
	v_mfma_f32_16x16x32_bf16 v[124:127], v[28:31], v[92:95], v[124:127]
	v_and_b32_e32 v190, v182, v190
	v_and_b32_e32 v191, v183, v191
	v_and_b32_e32 v192, v184, v192
	v_and_b32_e32 v193, v185, v193
	v_and_b32_e32 v194, v186, v194
	v_mfma_f32_16x16x32_bf16 v[120:123], v[24:27], v[92:95], v[120:123]
	v_and_b32_e32 v195, v187, v195
	v_cvt_pk_bf16_f32 v246, v188, v189
	v_cvt_pk_bf16_f32 v247, v190, v191
	v_cvt_pk_bf16_f32 v248, v192, v193
	v_cvt_pk_bf16_f32 v249, v194, v195
	v_mfma_f32_16x16x32_bf16 v[116:119], v[20:23], v[92:95], v[116:119]
	v_add_f32_e32 v1, v188, v189
	v_add_f32_e32 v2, v190, v191
	v_add_f32_e32 v3, v192, v193
	v_add_f32_e32 v85, v194, v195
	v_add_f32_e32 v1, v1, v2
	v_add_f32_e32 v3, v3, v85
	v_add_f32_e32 v1, v1, v3
	v_add_f32_e32 v225, v225, v1
	v_mfma_f32_16x16x32_bf16 v[112:115], v[32:35], v[246:249], v[112:115]
	v_mfma_f32_16x16x32_bf16 v[108:111], v[28:31], v[246:249], v[108:111]
	v_mfma_f32_16x16x32_bf16 v[104:107], v[24:27], v[246:249], v[104:107]
	v_mfma_f32_16x16x32_bf16 v[100:103], v[20:23], v[246:249], v[100:103]
	buffer_load_dwordx4 v[32:35], v234, s[40:43], s33 offen
	buffer_load_dwordx4 v[28:31], v82, s[40:43], s33 offen
	buffer_load_dwordx4 v[24:27], v83, s[40:43], s33 offen
	buffer_load_dwordx4 v[20:23], v84, s[40:43], s33 offen
	v_add_u32_e32 v240, 0x100, v240
	s_add_i32 s92, s92, 1
	s_add_i32 s20, s92, 2
	s_min_i32 s20, s20, s80
	s_add_i32 s21, s20, s77
	s_lshl_b32 s21, s21, 6
	s_or_b32 s21, s21, s59
	s_sub_i32 s22, s20, s76
	s_lshl_b32 s22, s22, 5
	s_addk_i32 s22, 0x1000
	s_cmp_lt_i32 s20, s76
	s_cselect_b32 s20, s21, s22
	s_lshl_b32 s23, s20, 10
	s_add_i32 s23, s23, s81
	s_lshl_b32 s33, s20, 1
	s_add_i32 s33, s33, s82
	s_waitcnt vmcnt(12)
	ds_read2_b32 v[204:205], v240 offset0:64 offset1:65
	ds_read2_b32 v[206:207], v240 offset0:66 offset1:67
	ds_read2_b32 v[208:209], v240 offset0:68 offset1:69
	ds_read2_b32 v[210:211], v240 offset0:70 offset1:71
	ds_read2_b32 v[212:213], v240 offset0:0 offset1:1
	ds_read2_b32 v[214:215], v240 offset0:2 offset1:3
	ds_read2_b32 v[242:243], v240 offset0:4 offset1:5
	ds_read2_b32 v[244:245], v240 offset0:6 offset1:7
	v_mfma_f32_16x16x32_bf16 v[188:191], v[48:51], v[148:151], v[76:79]
	v_mfma_f32_16x16x32_bf16 v[192:195], v[40:43], v[148:151], v[76:79]
	v_mfma_f32_16x16x32_bf16 v[188:191], v[44:47], v[152:155], v[188:191]
	v_mfma_f32_16x16x32_bf16 v[192:195], v[36:39], v[152:155], v[192:195]
	v_mfma_f32_16x16x32_bf16 v[196:199], v[48:51], v[156:159], v[76:79]
	v_mfma_f32_16x16x32_bf16 v[200:203], v[40:43], v[156:159], v[76:79]
	v_mfma_f32_16x16x32_bf16 v[196:199], v[44:47], v[160:163], v[196:199]
	v_mfma_f32_16x16x32_bf16 v[200:203], v[36:39], v[160:163], v[200:203]
	buffer_load_dwordx4 v[48:51], v233, s[24:27], s23 offen
	buffer_load_dwordx4 v[44:47], v235, s[24:27], s23 offen
	buffer_load_dwordx4 v[40:43], v80, s[24:27], s23 offen
	buffer_load_dwordx4 v[36:39], v81, s[24:27], s23 offen
	s_waitcnt lgkmcnt(4)
	v_add_f32_e32 v188, v188, v204
	v_add_f32_e32 v189, v189, v205
	v_add_f32_e32 v190, v190, v206
	v_add_f32_e32 v191, v191, v207
	v_add_f32_e32 v192, v192, v208
	v_add_f32_e32 v193, v193, v209
	v_add_f32_e32 v194, v194, v210
	v_add_f32_e32 v195, v195, v211
	v_exp_f32_e32 v188, v188
	v_exp_f32_e32 v189, v189
	v_exp_f32_e32 v190, v190
	v_exp_f32_e32 v191, v191
	v_exp_f32_e32 v192, v192
	v_exp_f32_e32 v193, v193
	v_exp_f32_e32 v194, v194
	v_exp_f32_e32 v195, v195
	v_and_b32_e32 v188, v180, v188
	v_and_b32_e32 v189, v181, v189
	v_and_b32_e32 v190, v182, v190
	v_and_b32_e32 v191, v183, v191
	v_and_b32_e32 v192, v184, v192
	v_and_b32_e32 v193, v185, v193
	v_and_b32_e32 v194, v186, v194
	v_and_b32_e32 v195, v187, v195
	v_cvt_pk_bf16_f32 v246, v188, v189
	v_cvt_pk_bf16_f32 v247, v190, v191
	v_cvt_pk_bf16_f32 v248, v192, v193
	v_cvt_pk_bf16_f32 v249, v194, v195
	v_add_f32_e32 v1, v188, v189
	v_add_f32_e32 v2, v190, v191
	v_add_f32_e32 v3, v192, v193
	v_add_f32_e32 v85, v194, v195
	v_add_f32_e32 v1, v1, v2
	v_add_f32_e32 v3, v3, v85
	v_add_f32_e32 v1, v1, v3
	v_add_f32_e32 v224, v224, v1
	s_waitcnt vmcnt(12)
	s_waitcnt lgkmcnt(0)
	v_add_f32_e32 v196, v196, v212
	v_add_f32_e32 v197, v197, v213
	v_add_f32_e32 v198, v198, v214
	v_add_f32_e32 v199, v199, v215
	v_add_f32_e32 v200, v200, v242
	v_add_f32_e32 v201, v201, v243
	v_add_f32_e32 v202, v202, v244
	v_add_f32_e32 v203, v203, v245
	v_exp_f32_e32 v196, v196
	v_exp_f32_e32 v197, v197
	v_exp_f32_e32 v198, v198
	v_exp_f32_e32 v199, v199
	v_exp_f32_e32 v200, v200
	v_mfma_f32_16x16x32_bf16 v[128:131], v[16:19], v[246:249], v[128:131]
	v_exp_f32_e32 v201, v201
	v_exp_f32_e32 v202, v202
	v_exp_f32_e32 v203, v203
	v_and_b32_e32 v196, v180, v196
	v_and_b32_e32 v197, v181, v197
	v_mfma_f32_16x16x32_bf16 v[124:127], v[12:15], v[246:249], v[124:127]
	v_and_b32_e32 v198, v182, v198
	v_and_b32_e32 v199, v183, v199
	v_and_b32_e32 v200, v184, v200
	v_and_b32_e32 v201, v185, v201
	v_and_b32_e32 v202, v186, v202
	v_mfma_f32_16x16x32_bf16 v[120:123], v[8:11], v[246:249], v[120:123]
	v_and_b32_e32 v203, v187, v203
	v_cvt_pk_bf16_f32 v92, v196, v197
	v_cvt_pk_bf16_f32 v93, v198, v199
	v_cvt_pk_bf16_f32 v94, v200, v201
	v_cvt_pk_bf16_f32 v95, v202, v203
	v_mfma_f32_16x16x32_bf16 v[116:119], v[4:7], v[246:249], v[116:119]
	v_add_f32_e32 v86, v196, v197
	v_add_f32_e32 v87, v198, v199
	v_add_f32_e32 v220, v200, v201
	v_add_f32_e32 v221, v202, v203
	v_add_f32_e32 v86, v86, v87
	v_add_f32_e32 v220, v220, v221
	v_add_f32_e32 v86, v86, v220
	v_add_f32_e32 v225, v225, v86
	v_mfma_f32_16x16x32_bf16 v[112:115], v[16:19], v[92:95], v[112:115]
	v_mfma_f32_16x16x32_bf16 v[108:111], v[12:15], v[92:95], v[108:111]
	v_mfma_f32_16x16x32_bf16 v[104:107], v[8:11], v[92:95], v[104:107]
	v_mfma_f32_16x16x32_bf16 v[100:103], v[4:7], v[92:95], v[100:103]
	buffer_load_dwordx4 v[16:19], v234, s[40:43], s33 offen
	buffer_load_dwordx4 v[12:15], v82, s[40:43], s33 offen
	buffer_load_dwordx4 v[8:11], v83, s[40:43], s33 offen
	buffer_load_dwordx4 v[4:7], v84, s[40:43], s33 offen
	v_add_u32_e32 v240, 0x100, v240
	s_add_i32 s92, s92, 1
	s_add_i32 s20, s92, 2
	s_min_i32 s20, s20, s80
	s_add_i32 s21, s20, s77
	s_lshl_b32 s21, s21, 6
	s_or_b32 s21, s21, s59
	s_sub_i32 s22, s20, s76
	s_lshl_b32 s22, s22, 5
	s_addk_i32 s22, 0x1000
	s_cmp_lt_i32 s20, s76
	s_cselect_b32 s20, s21, s22
	s_lshl_b32 s23, s20, 10
	s_add_i32 s23, s23, s81
	s_lshl_b32 s33, s20, 1
	s_add_i32 s33, s33, s82
	s_waitcnt vmcnt(12)
	ds_read2_b32 v[204:205], v240 offset0:0 offset1:1
	ds_read2_b32 v[206:207], v240 offset0:2 offset1:3
	ds_read2_b32 v[208:209], v240 offset0:4 offset1:5
	ds_read2_b32 v[210:211], v240 offset0:6 offset1:7
	v_mfma_f32_16x16x32_bf16 v[188:191], v[176:179], v[156:159], v[76:79]
	v_mfma_f32_16x16x32_bf16 v[192:195], v[168:171], v[156:159], v[76:79]
	v_mfma_f32_16x16x32_bf16 v[188:191], v[172:175], v[160:163], v[188:191]
	v_mfma_f32_16x16x32_bf16 v[192:195], v[164:167], v[160:163], v[192:195]
	buffer_load_dwordx4 v[176:179], v233, s[24:27], s23 offen
	buffer_load_dwordx4 v[172:175], v235, s[24:27], s23 offen
	buffer_load_dwordx4 v[168:171], v80, s[24:27], s23 offen
	buffer_load_dwordx4 v[164:167], v81, s[24:27], s23 offen
	s_waitcnt lgkmcnt(0)
	s_nop 1
	v_add_f32_e32 v188, v188, v204
	v_add_f32_e32 v189, v189, v205
	v_add_f32_e32 v190, v190, v206
	v_add_f32_e32 v191, v191, v207
	v_add_f32_e32 v192, v192, v208
	v_add_f32_e32 v193, v193, v209
	v_add_f32_e32 v194, v194, v210
	v_add_f32_e32 v195, v195, v211
	v_exp_f32_e32 v188, v188
	v_exp_f32_e32 v189, v189
	v_exp_f32_e32 v190, v190
	v_exp_f32_e32 v191, v191
	v_exp_f32_e32 v192, v192
	v_exp_f32_e32 v193, v193
	v_exp_f32_e32 v194, v194
	v_exp_f32_e32 v195, v195
	v_and_b32_e32 v188, v180, v188
	v_and_b32_e32 v189, v181, v189
	v_and_b32_e32 v190, v182, v190
	v_and_b32_e32 v191, v183, v191
	v_and_b32_e32 v192, v184, v192
	v_and_b32_e32 v193, v185, v193
	v_and_b32_e32 v194, v186, v194
	v_and_b32_e32 v195, v187, v195
	v_cvt_pk_bf16_f32 v246, v188, v189
	v_cvt_pk_bf16_f32 v247, v190, v191
	v_cvt_pk_bf16_f32 v248, v192, v193
	v_cvt_pk_bf16_f32 v249, v194, v195
	v_add_f32_e32 v1, v188, v189
	v_add_f32_e32 v2, v190, v191
	v_add_f32_e32 v3, v192, v193
	v_add_f32_e32 v85, v194, v195
	v_add_f32_e32 v1, v1, v2
	v_add_f32_e32 v3, v3, v85
	v_add_f32_e32 v1, v1, v3
	v_add_f32_e32 v225, v225, v1
	s_waitcnt vmcnt(12)
	v_mfma_f32_16x16x32_bf16 v[112:115], v[32:35], v[246:249], v[112:115]
	v_mfma_f32_16x16x32_bf16 v[108:111], v[28:31], v[246:249], v[108:111]
	v_mfma_f32_16x16x32_bf16 v[104:107], v[24:27], v[246:249], v[104:107]
	v_mfma_f32_16x16x32_bf16 v[100:103], v[20:23], v[246:249], v[100:103]
	buffer_load_dwordx4 v[32:35], v234, s[40:43], s33 offen
	buffer_load_dwordx4 v[28:31], v82, s[40:43], s33 offen
	buffer_load_dwordx4 v[24:27], v83, s[40:43], s33 offen
	buffer_load_dwordx4 v[20:23], v84, s[40:43], s33 offen
	v_add_u32_e32 v240, 0x100, v240
	s_add_i32 s92, s92, 1
	s_mov_b32 s91, 8
	s_branch .Latt_CB

.Latt_CA:
	s_add_i32 s20, s92, 2
	s_min_i32 s20, s20, s80
	s_add_i32 s21, s20, s77
	s_lshl_b32 s21, s21, 6
	s_or_b32 s21, s21, s59
	s_sub_i32 s22, s20, s76
	s_lshl_b32 s22, s22, 5
	s_addk_i32 s22, 0x1000
	s_cmp_lt_i32 s20, s76
	s_cselect_b32 s20, s21, s22
	s_lshl_b32 s23, s20, 10
	s_add_i32 s23, s23, s81
	s_lshl_b32 s33, s20, 1
	s_add_i32 s33, s33, s82
	s_waitcnt vmcnt(12)
	v_mfma_f32_16x16x32_bf16 v[188:191], v[176:179], v[132:135], v[76:79]
	v_mfma_f32_16x16x32_bf16 v[192:195], v[168:171], v[132:135], v[76:79]
	v_mfma_f32_16x16x32_bf16 v[188:191], v[172:175], v[136:139], v[188:191]
	v_mfma_f32_16x16x32_bf16 v[192:195], v[164:167], v[136:139], v[192:195]
	v_mfma_f32_16x16x32_bf16 v[196:199], v[176:179], v[140:143], v[76:79]
	v_mfma_f32_16x16x32_bf16 v[200:203], v[168:171], v[140:143], v[76:79]
	v_mfma_f32_16x16x32_bf16 v[196:199], v[172:175], v[144:147], v[196:199]
	v_mfma_f32_16x16x32_bf16 v[200:203], v[164:167], v[144:147], v[200:203]
	s_nop 2
	v_exp_f32_e32 v188, v188
	v_exp_f32_e32 v189, v189
	v_exp_f32_e32 v190, v190
	v_exp_f32_e32 v191, v191
	v_exp_f32_e32 v192, v192
	v_exp_f32_e32 v193, v193
	v_exp_f32_e32 v194, v194
	v_exp_f32_e32 v195, v195
	v_cvt_pk_bf16_f32 v246, v188, v189
	v_cvt_pk_bf16_f32 v247, v190, v191
	v_cvt_pk_bf16_f32 v248, v192, v193
	v_cvt_pk_bf16_f32 v249, v194, v195
	v_add_f32_e32 v1, v188, v189
	v_add_f32_e32 v2, v190, v191
	v_add_f32_e32 v3, v192, v193
	v_add_f32_e32 v85, v194, v195
	v_add_f32_e32 v1, v1, v2
	v_add_f32_e32 v3, v3, v85
	v_add_f32_e32 v1, v1, v3
	v_add_f32_e32 v222, v222, v1
	v_mfma_f32_16x16x32_bf16 v[188:191], v[176:179], v[148:151], v[76:79]
	v_mfma_f32_16x16x32_bf16 v[192:195], v[168:171], v[148:151], v[76:79]
	v_mfma_f32_16x16x32_bf16 v[188:191], v[172:175], v[152:155], v[188:191]
	v_mfma_f32_16x16x32_bf16 v[192:195], v[164:167], v[152:155], v[192:195]
	s_waitcnt vmcnt(8)
	v_exp_f32_e32 v196, v196
	v_exp_f32_e32 v197, v197
	v_exp_f32_e32 v198, v198
	v_exp_f32_e32 v199, v199
	v_mfma_f32_16x16x32_bf16 v[96:99], v[32:35], v[246:249], v[96:99]
	v_exp_f32_e32 v200, v200
	v_exp_f32_e32 v201, v201
	v_exp_f32_e32 v202, v202
	v_exp_f32_e32 v203, v203
	v_mfma_f32_16x16x32_bf16 v[88:91], v[28:31], v[246:249], v[88:91]
	v_cvt_pk_bf16_f32 v92, v196, v197
	v_cvt_pk_bf16_f32 v93, v198, v199
	v_cvt_pk_bf16_f32 v94, v200, v201
	v_cvt_pk_bf16_f32 v95, v202, v203
	v_mfma_f32_16x16x32_bf16 v[72:75], v[24:27], v[246:249], v[72:75]
	v_add_f32_e32 v86, v196, v197
	v_add_f32_e32 v87, v198, v199
	v_add_f32_e32 v220, v200, v201
	v_add_f32_e32 v221, v202, v203
	v_mfma_f32_16x16x32_bf16 v[68:71], v[20:23], v[246:249], v[68:71]
	v_add_f32_e32 v86, v86, v87
	v_add_f32_e32 v220, v220, v221
	v_add_f32_e32 v86, v86, v220
	v_add_f32_e32 v223, v223, v86
	v_mfma_f32_16x16x32_bf16 v[196:199], v[176:179], v[156:159], v[76:79]
	v_mfma_f32_16x16x32_bf16 v[200:203], v[168:171], v[156:159], v[76:79]
	v_mfma_f32_16x16x32_bf16 v[196:199], v[172:175], v[160:163], v[196:199]
	v_mfma_f32_16x16x32_bf16 v[200:203], v[164:167], v[160:163], v[200:203]
	buffer_load_dwordx4 v[176:179], v233, s[24:27], s23 offen
	buffer_load_dwordx4 v[172:175], v235, s[24:27], s23 offen
	buffer_load_dwordx4 v[168:171], v80, s[24:27], s23 offen
	buffer_load_dwordx4 v[164:167], v81, s[24:27], s23 offen
	v_exp_f32_e32 v188, v188
	v_exp_f32_e32 v189, v189
	v_exp_f32_e32 v190, v190
	v_exp_f32_e32 v191, v191
	v_mfma_f32_16x16x32_bf16 v[64:67], v[32:35], v[92:95], v[64:67]
	v_exp_f32_e32 v192, v192
	v_exp_f32_e32 v193, v193
	v_exp_f32_e32 v194, v194
	v_exp_f32_e32 v195, v195
	v_mfma_f32_16x16x32_bf16 v[60:63], v[28:31], v[92:95], v[60:63]
	v_cvt_pk_bf16_f32 v246, v188, v189
	v_cvt_pk_bf16_f32 v247, v190, v191
	v_cvt_pk_bf16_f32 v248, v192, v193
	v_cvt_pk_bf16_f32 v249, v194, v195
	v_mfma_f32_16x16x32_bf16 v[56:59], v[24:27], v[92:95], v[56:59]
	v_add_f32_e32 v1, v188, v189
	v_add_f32_e32 v2, v190, v191
	v_add_f32_e32 v3, v192, v193
	v_add_f32_e32 v85, v194, v195
	v_mfma_f32_16x16x32_bf16 v[52:55], v[20:23], v[92:95], v[52:55]
	v_add_f32_e32 v1, v1, v2
	v_add_f32_e32 v3, v3, v85
	v_add_f32_e32 v1, v1, v3
	v_add_f32_e32 v224, v224, v1
	v_exp_f32_e32 v196, v196
	v_exp_f32_e32 v197, v197
	v_exp_f32_e32 v198, v198
	v_exp_f32_e32 v199, v199
	v_mfma_f32_16x16x32_bf16 v[128:131], v[32:35], v[246:249], v[128:131]
	v_exp_f32_e32 v200, v200
	v_exp_f32_e32 v201, v201
	v_exp_f32_e32 v202, v202
	v_exp_f32_e32 v203, v203
	v_mfma_f32_16x16x32_bf16 v[124:127], v[28:31], v[246:249], v[124:127]
	v_cvt_pk_bf16_f32 v92, v196, v197
	v_cvt_pk_bf16_f32 v93, v198, v199
	v_cvt_pk_bf16_f32 v94, v200, v201
	v_cvt_pk_bf16_f32 v95, v202, v203
	v_mfma_f32_16x16x32_bf16 v[120:123], v[24:27], v[246:249], v[120:123]
	v_add_f32_e32 v86, v196, v197
	v_add_f32_e32 v87, v198, v199
	v_add_f32_e32 v220, v200, v201
	v_add_f32_e32 v221, v202, v203
	v_mfma_f32_16x16x32_bf16 v[116:119], v[20:23], v[246:249], v[116:119]
	v_add_f32_e32 v86, v86, v87
	v_add_f32_e32 v220, v220, v221
	v_add_f32_e32 v86, v86, v220
	v_add_f32_e32 v225, v225, v86
	v_mfma_f32_16x16x32_bf16 v[112:115], v[32:35], v[92:95], v[112:115]
	v_mfma_f32_16x16x32_bf16 v[108:111], v[28:31], v[92:95], v[108:111]
	v_mfma_f32_16x16x32_bf16 v[104:107], v[24:27], v[92:95], v[104:107]
	v_mfma_f32_16x16x32_bf16 v[100:103], v[20:23], v[92:95], v[100:103]
	buffer_load_dwordx4 v[32:35], v234, s[40:43], s33 offen
	buffer_load_dwordx4 v[28:31], v82, s[40:43], s33 offen
	buffer_load_dwordx4 v[24:27], v83, s[40:43], s33 offen
	buffer_load_dwordx4 v[20:23], v84, s[40:43], s33 offen
	s_add_i32 s92, s92, 1
	s_sub_u32 s91, s91, 1
	s_cmp_eq_u32 s91, 0
	s_cbranch_scc1 .Latt_done
.Latt_CB:
	s_add_i32 s20, s92, 2
	s_min_i32 s20, s20, s80
	s_add_i32 s21, s20, s77
	s_lshl_b32 s21, s21, 6
	s_or_b32 s21, s21, s59
	s_sub_i32 s22, s20, s76
	s_lshl_b32 s22, s22, 5
	s_addk_i32 s22, 0x1000
	s_cmp_lt_i32 s20, s76
	s_cselect_b32 s20, s21, s22
	s_lshl_b32 s23, s20, 10
	s_add_i32 s23, s23, s81
	s_lshl_b32 s33, s20, 1
	s_add_i32 s33, s33, s82
	s_waitcnt vmcnt(12)
	v_mfma_f32_16x16x32_bf16 v[188:191], v[48:51], v[132:135], v[76:79]
	v_mfma_f32_16x16x32_bf16 v[192:195], v[40:43], v[132:135], v[76:79]
	v_mfma_f32_16x16x32_bf16 v[188:191], v[44:47], v[136:139], v[188:191]
	v_mfma_f32_16x16x32_bf16 v[192:195], v[36:39], v[136:139], v[192:195]
	v_mfma_f32_16x16x32_bf16 v[196:199], v[48:51], v[140:143], v[76:79]
	v_mfma_f32_16x16x32_bf16 v[200:203], v[40:43], v[140:143], v[76:79]
	v_mfma_f32_16x16x32_bf16 v[196:199], v[44:47], v[144:147], v[196:199]
	v_mfma_f32_16x16x32_bf16 v[200:203], v[36:39], v[144:147], v[200:203]
	s_nop 2
	v_exp_f32_e32 v188, v188
	v_exp_f32_e32 v189, v189
	v_exp_f32_e32 v190, v190
	v_exp_f32_e32 v191, v191
	v_exp_f32_e32 v192, v192
	v_exp_f32_e32 v193, v193
	v_exp_f32_e32 v194, v194
	v_exp_f32_e32 v195, v195
	v_cvt_pk_bf16_f32 v246, v188, v189
	v_cvt_pk_bf16_f32 v247, v190, v191
	v_cvt_pk_bf16_f32 v248, v192, v193
	v_cvt_pk_bf16_f32 v249, v194, v195
	v_add_f32_e32 v1, v188, v189
	v_add_f32_e32 v2, v190, v191
	v_add_f32_e32 v3, v192, v193
	v_add_f32_e32 v85, v194, v195
	v_add_f32_e32 v1, v1, v2
	v_add_f32_e32 v3, v3, v85
	v_add_f32_e32 v1, v1, v3
	v_add_f32_e32 v222, v222, v1
	v_mfma_f32_16x16x32_bf16 v[188:191], v[48:51], v[148:151], v[76:79]
	v_mfma_f32_16x16x32_bf16 v[192:195], v[40:43], v[148:151], v[76:79]
	v_mfma_f32_16x16x32_bf16 v[188:191], v[44:47], v[152:155], v[188:191]
	v_mfma_f32_16x16x32_bf16 v[192:195], v[36:39], v[152:155], v[192:195]
	s_waitcnt vmcnt(8)
	v_exp_f32_e32 v196, v196
	v_exp_f32_e32 v197, v197
	v_exp_f32_e32 v198, v198
	v_exp_f32_e32 v199, v199
	v_mfma_f32_16x16x32_bf16 v[96:99], v[16:19], v[246:249], v[96:99]
	v_exp_f32_e32 v200, v200
	v_exp_f32_e32 v201, v201
	v_exp_f32_e32 v202, v202
	v_exp_f32_e32 v203, v203
	v_mfma_f32_16x16x32_bf16 v[88:91], v[12:15], v[246:249], v[88:91]
	v_cvt_pk_bf16_f32 v92, v196, v197
	v_cvt_pk_bf16_f32 v93, v198, v199
	v_cvt_pk_bf16_f32 v94, v200, v201
	v_cvt_pk_bf16_f32 v95, v202, v203
	v_mfma_f32_16x16x32_bf16 v[72:75], v[8:11], v[246:249], v[72:75]
	v_add_f32_e32 v86, v196, v197
	v_add_f32_e32 v87, v198, v199
	v_add_f32_e32 v220, v200, v201
	v_add_f32_e32 v221, v202, v203
	v_mfma_f32_16x16x32_bf16 v[68:71], v[4:7], v[246:249], v[68:71]
	v_add_f32_e32 v86, v86, v87
	v_add_f32_e32 v220, v220, v221
	v_add_f32_e32 v86, v86, v220
	v_add_f32_e32 v223, v223, v86
	v_mfma_f32_16x16x32_bf16 v[196:199], v[48:51], v[156:159], v[76:79]
	v_mfma_f32_16x16x32_bf16 v[200:203], v[40:43], v[156:159], v[76:79]
	v_mfma_f32_16x16x32_bf16 v[196:199], v[44:47], v[160:163], v[196:199]
	v_mfma_f32_16x16x32_bf16 v[200:203], v[36:39], v[160:163], v[200:203]
	buffer_load_dwordx4 v[48:51], v233, s[24:27], s23 offen
	buffer_load_dwordx4 v[44:47], v235, s[24:27], s23 offen
	buffer_load_dwordx4 v[40:43], v80, s[24:27], s23 offen
	buffer_load_dwordx4 v[36:39], v81, s[24:27], s23 offen
	v_exp_f32_e32 v188, v188
	v_exp_f32_e32 v189, v189
	v_exp_f32_e32 v190, v190
	v_exp_f32_e32 v191, v191
	v_mfma_f32_16x16x32_bf16 v[64:67], v[16:19], v[92:95], v[64:67]
	v_exp_f32_e32 v192, v192
	v_exp_f32_e32 v193, v193
	v_exp_f32_e32 v194, v194
	v_exp_f32_e32 v195, v195
	v_mfma_f32_16x16x32_bf16 v[60:63], v[12:15], v[92:95], v[60:63]
	v_cvt_pk_bf16_f32 v246, v188, v189
	v_cvt_pk_bf16_f32 v247, v190, v191
	v_cvt_pk_bf16_f32 v248, v192, v193
	v_cvt_pk_bf16_f32 v249, v194, v195
	v_mfma_f32_16x16x32_bf16 v[56:59], v[8:11], v[92:95], v[56:59]
	v_add_f32_e32 v1, v188, v189
	v_add_f32_e32 v2, v190, v191
	v_add_f32_e32 v3, v192, v193
	v_add_f32_e32 v85, v194, v195
	v_mfma_f32_16x16x32_bf16 v[52:55], v[4:7], v[92:95], v[52:55]
	v_add_f32_e32 v1, v1, v2
	v_add_f32_e32 v3, v3, v85
	v_add_f32_e32 v1, v1, v3
	v_add_f32_e32 v224, v224, v1
	v_exp_f32_e32 v196, v196
	v_exp_f32_e32 v197, v197
	v_exp_f32_e32 v198, v198
	v_exp_f32_e32 v199, v199
	v_mfma_f32_16x16x32_bf16 v[128:131], v[16:19], v[246:249], v[128:131]
	v_exp_f32_e32 v200, v200
	v_exp_f32_e32 v201, v201
	v_exp_f32_e32 v202, v202
	v_exp_f32_e32 v203, v203
	v_mfma_f32_16x16x32_bf16 v[124:127], v[12:15], v[246:249], v[124:127]
	v_cvt_pk_bf16_f32 v92, v196, v197
	v_cvt_pk_bf16_f32 v93, v198, v199
	v_cvt_pk_bf16_f32 v94, v200, v201
	v_cvt_pk_bf16_f32 v95, v202, v203
	v_mfma_f32_16x16x32_bf16 v[120:123], v[8:11], v[246:249], v[120:123]
	v_add_f32_e32 v86, v196, v197
	v_add_f32_e32 v87, v198, v199
	v_add_f32_e32 v220, v200, v201
	v_add_f32_e32 v221, v202, v203
	v_mfma_f32_16x16x32_bf16 v[116:119], v[4:7], v[246:249], v[116:119]
	v_add_f32_e32 v86, v86, v87
	v_add_f32_e32 v220, v220, v221
	v_add_f32_e32 v86, v86, v220
	v_add_f32_e32 v225, v225, v86
	v_mfma_f32_16x16x32_bf16 v[112:115], v[16:19], v[92:95], v[112:115]
	v_mfma_f32_16x16x32_bf16 v[108:111], v[12:15], v[92:95], v[108:111]
	v_mfma_f32_16x16x32_bf16 v[104:107], v[8:11], v[92:95], v[104:107]
	v_mfma_f32_16x16x32_bf16 v[100:103], v[4:7], v[92:95], v[100:103]
	buffer_load_dwordx4 v[16:19], v234, s[40:43], s33 offen
	buffer_load_dwordx4 v[12:15], v82, s[40:43], s33 offen
	buffer_load_dwordx4 v[8:11], v83, s[40:43], s33 offen
	buffer_load_dwordx4 v[4:7], v84, s[40:43], s33 offen
	s_add_i32 s92, s92, 1
	s_sub_u32 s91, s91, 1
	s_cmp_lg_u32 s91, 0
	s_cbranch_scc1 .Latt_CA
.Latt_done:
	s_nop 7
	s_branch .LBB0_450
